# realign barrier of the leading GEMM half moved ~64 (SwiGLU) / ~48 instructions down into the epilogue: its epilogue VALU starts while the trailing half still runs its last MFMA block
# speedup vs baseline: 1.0008x; 1.0008x over previous
.LBB0_187:
	v_mul_f32_e32 v151, 0xbfb8aa3b, v124
	v_exp_f32_e32 v151, v151
	v_mul_f32_e32 v154, 0xbfb8aa3b, v125
	v_exp_f32_e32 v154, v154
	v_lshl_or_b32 v142, s65, 7, v146
	v_add_f32_e32 v151, 1.0, v151
	v_rcp_f32_e32 v151, v151
	v_lshl_add_u32 v150, s36, 8, v144
	v_ashrrev_i32_e32 v143, 31, v142
	v_mov_b64_e32 v[140:141], s[22:23]
	v_mul_f32_e32 v124, v124, v151
	v_mul_f32_e32 v120, v120, v124
	v_add_f32_e32 v124, 1.0, v154
	v_mul_f32_e32 v151, 0xbfb8aa3b, v126
	v_rcp_f32_e32 v124, v124
	v_exp_f32_e32 v151, v151
	v_mul_f32_e32 v154, 0xbfb8aa3b, v127
	v_exp_f32_e32 v154, v154
	v_mul_f32_e32 v124, v125, v124
	v_add_f32_e32 v125, 1.0, v151
	v_rcp_f32_e32 v125, v125
	v_add_f32_e32 v151, 1.0, v154
	v_rcp_f32_e32 v151, v151
	v_mul_f32_e32 v121, v121, v124
	v_mul_f32_e32 v124, v126, v125
	v_mul_f32_e32 v125, 0xbfb8aa3b, v116
	v_exp_f32_e32 v125, v125
	v_mul_f32_e32 v122, v122, v124
	v_mul_f32_e32 v124, v127, v151
	v_mul_f32_e32 v123, v123, v124
	v_cvt_pk_bf16_f32 v120, v120, v121
	v_cvt_pk_bf16_f32 v121, v122, v123
	v_add_f32_e32 v122, 1.0, v125
	v_rcp_f32_e32 v122, v122
	v_mul_f32_e32 v123, 0xbfb8aa3b, v117
	v_exp_f32_e32 v123, v123
	v_mad_i64_i32 v[152:153], s[44:45], v150, s64, v[140:141]
	v_lshlrev_b64 v[142:143], 1, v[142:143]
	v_lshl_add_u64 v[152:153], v[152:153], 0, v[142:143]
	v_mul_f32_e32 v116, v116, v122
	global_store_dwordx2 v[152:153], v[120:121], off
	v_mul_f32_e32 v112, v112, v116
	v_add_f32_e32 v116, 1.0, v123
	v_mul_f32_e32 v120, 0xbfb8aa3b, v118
	v_rcp_f32_e32 v116, v116
	v_exp_f32_e32 v120, v120
	v_mul_f32_e32 v121, 0xbfb8aa3b, v119
	v_exp_f32_e32 v121, v121
	v_mul_f32_e32 v116, v117, v116
	v_add_f32_e32 v117, 1.0, v120
	v_rcp_f32_e32 v117, v117
	v_add_f32_e32 v120, 1.0, v121
	v_rcp_f32_e32 v120, v120
	v_mul_f32_e32 v113, v113, v116
	v_mul_f32_e32 v116, v118, v117
	v_mul_f32_e32 v114, v114, v116
	v_mul_f32_e32 v116, v119, v120
	v_cvt_pk_bf16_f32 v112, v112, v113
	v_mul_f32_e32 v115, v115, v116
	v_cvt_pk_bf16_f32 v113, v114, v115
	global_store_dwordx2 v[152:153], v[112:113], off offset:128
	v_mul_f32_e32 v112, 0xbfb8aa3b, v108
	v_exp_f32_e32 v114, v112
	v_mul_f32_e32 v115, 0xbfb8aa3b, v109
	s_and_b64 vcc, exec, s[8:9]
	s_cbranch_vccz .Lxb_0
	s_barrier
.Lxb_0:
	v_exp_f32_e32 v115, v115
	v_or_b32_e32 v112, 16, v150
	v_add_f32_e32 v114, 1.0, v114
	v_rcp_f32_e32 v114, v114
	v_mad_i64_i32 v[112:113], s[44:45], v112, s64, v[140:141]
	v_lshl_add_u64 v[112:113], v[112:113], 0, v[142:143]
	v_mul_f32_e32 v108, v108, v114
	v_mul_f32_e32 v104, v104, v108
	v_add_f32_e32 v108, 1.0, v115
	v_mul_f32_e32 v114, 0xbfb8aa3b, v110
	v_rcp_f32_e32 v108, v108
	v_exp_f32_e32 v114, v114
	v_mul_f32_e32 v115, 0xbfb8aa3b, v111
	v_exp_f32_e32 v115, v115
	v_mul_f32_e32 v108, v109, v108
	v_add_f32_e32 v109, 1.0, v114
	v_rcp_f32_e32 v109, v109
	v_add_f32_e32 v114, 1.0, v115
	v_rcp_f32_e32 v114, v114
	v_mul_f32_e32 v105, v105, v108
	v_mul_f32_e32 v108, v110, v109
	v_mul_f32_e32 v109, 0xbfb8aa3b, v100
	v_exp_f32_e32 v109, v109
	v_mul_f32_e32 v106, v106, v108
	v_mul_f32_e32 v108, v111, v114
	v_mul_f32_e32 v107, v107, v108
	v_cvt_pk_bf16_f32 v104, v104, v105
	v_cvt_pk_bf16_f32 v105, v106, v107
	v_add_f32_e32 v106, 1.0, v109
	v_rcp_f32_e32 v106, v106
	v_mul_f32_e32 v107, 0xbfb8aa3b, v101
	v_exp_f32_e32 v107, v107
	global_store_dwordx2 v[112:113], v[104:105], off
	v_mul_f32_e32 v100, v100, v106
	v_mul_f32_e32 v96, v96, v100
	v_add_f32_e32 v100, 1.0, v107
	v_mul_f32_e32 v104, 0xbfb8aa3b, v102
	v_rcp_f32_e32 v100, v100
	v_exp_f32_e32 v104, v104
	v_mul_f32_e32 v105, 0xbfb8aa3b, v103
	v_exp_f32_e32 v105, v105
	v_mul_f32_e32 v100, v101, v100
	v_add_f32_e32 v101, 1.0, v104
	v_rcp_f32_e32 v101, v101
	v_add_f32_e32 v104, 1.0, v105
	v_rcp_f32_e32 v104, v104
	v_mul_f32_e32 v97, v97, v100
	v_mul_f32_e32 v100, v102, v101
	v_mul_f32_e32 v98, v98, v100
	v_mul_f32_e32 v100, v103, v104
	v_cvt_pk_bf16_f32 v96, v96, v97
	v_mul_f32_e32 v99, v99, v100
	v_cvt_pk_bf16_f32 v97, v98, v99
	global_store_dwordx2 v[112:113], v[96:97], off offset:128
	v_mul_f32_e32 v96, 0xbfb8aa3b, v92
	v_exp_f32_e32 v98, v96
	v_mul_f32_e32 v99, 0xbfb8aa3b, v93
	v_exp_f32_e32 v99, v99
	v_or_b32_e32 v96, 32, v150
	v_add_f32_e32 v98, 1.0, v98
	v_rcp_f32_e32 v98, v98
	v_mad_i64_i32 v[96:97], s[44:45], v96, s64, v[140:141]
	v_lshl_add_u64 v[96:97], v[96:97], 0, v[142:143]
	v_mul_f32_e32 v92, v92, v98
	v_mul_f32_e32 v88, v88, v92
	v_add_f32_e32 v92, 1.0, v99
	v_mul_f32_e32 v98, 0xbfb8aa3b, v94
	v_rcp_f32_e32 v92, v92
	v_exp_f32_e32 v98, v98
	v_mul_f32_e32 v99, 0xbfb8aa3b, v95
	v_exp_f32_e32 v99, v99
	v_mul_f32_e32 v92, v93, v92
	v_add_f32_e32 v93, 1.0, v98
	v_rcp_f32_e32 v93, v93
	v_add_f32_e32 v98, 1.0, v99
	v_rcp_f32_e32 v98, v98
	v_mul_f32_e32 v89, v89, v92
	v_mul_f32_e32 v92, v94, v93
	v_mul_f32_e32 v93, 0xbfb8aa3b, v84
	v_exp_f32_e32 v93, v93
	v_mul_f32_e32 v90, v90, v92
	v_mul_f32_e32 v92, v95, v98
	v_mul_f32_e32 v91, v91, v92
	v_cvt_pk_bf16_f32 v88, v88, v89
	v_cvt_pk_bf16_f32 v89, v90, v91
	v_add_f32_e32 v90, 1.0, v93
	v_rcp_f32_e32 v90, v90
	v_mul_f32_e32 v91, 0xbfb8aa3b, v85
	v_exp_f32_e32 v91, v91
	global_store_dwordx2 v[96:97], v[88:89], off
	v_mul_f32_e32 v84, v84, v90
	v_mul_f32_e32 v80, v80, v84
	v_add_f32_e32 v84, 1.0, v91
	v_mul_f32_e32 v88, 0xbfb8aa3b, v86
	v_rcp_f32_e32 v84, v84
	v_exp_f32_e32 v88, v88
	v_mul_f32_e32 v89, 0xbfb8aa3b, v87
	v_exp_f32_e32 v89, v89
	v_mul_f32_e32 v84, v85, v84
	v_add_f32_e32 v85, 1.0, v88
	v_rcp_f32_e32 v85, v85
	v_add_f32_e32 v88, 1.0, v89
	v_rcp_f32_e32 v88, v88
	v_mul_f32_e32 v81, v81, v84
	v_mul_f32_e32 v84, v86, v85
	v_mul_f32_e32 v82, v82, v84
	v_mul_f32_e32 v84, v87, v88
	v_cvt_pk_bf16_f32 v80, v80, v81
	v_mul_f32_e32 v83, v83, v84
	v_cvt_pk_bf16_f32 v81, v82, v83
	global_store_dwordx2 v[96:97], v[80:81], off offset:128
	v_mul_f32_e32 v80, 0xbfb8aa3b, v76
	v_exp_f32_e32 v82, v80
	v_mul_f32_e32 v83, 0xbfb8aa3b, v77
	v_exp_f32_e32 v83, v83
	v_or_b32_e32 v80, 48, v150
	v_add_f32_e32 v82, 1.0, v82
	v_rcp_f32_e32 v82, v82
	v_mad_i64_i32 v[80:81], s[44:45], v80, s64, v[140:141]
	v_lshl_add_u64 v[80:81], v[80:81], 0, v[142:143]
	v_mul_f32_e32 v76, v76, v82
	v_mul_f32_e32 v72, v72, v76
	v_add_f32_e32 v76, 1.0, v83
	v_mul_f32_e32 v82, 0xbfb8aa3b, v78
	v_rcp_f32_e32 v76, v76
	v_exp_f32_e32 v82, v82
	v_mul_f32_e32 v83, 0xbfb8aa3b, v79
	v_exp_f32_e32 v83, v83
	v_mul_f32_e32 v76, v77, v76
	v_add_f32_e32 v77, 1.0, v82
	v_rcp_f32_e32 v77, v77
	v_add_f32_e32 v82, 1.0, v83
	v_rcp_f32_e32 v82, v82
	v_mul_f32_e32 v73, v73, v76
	v_mul_f32_e32 v76, v78, v77
	v_mul_f32_e32 v77, 0xbfb8aa3b, v68
	v_exp_f32_e32 v77, v77
	v_mul_f32_e32 v74, v74, v76
	v_mul_f32_e32 v76, v79, v82
	v_mul_f32_e32 v75, v75, v76
	v_cvt_pk_bf16_f32 v72, v72, v73
	v_cvt_pk_bf16_f32 v73, v74, v75
	v_add_f32_e32 v74, 1.0, v77
	v_rcp_f32_e32 v74, v74
	v_mul_f32_e32 v75, 0xbfb8aa3b, v69
	v_exp_f32_e32 v75, v75
	global_store_dwordx2 v[80:81], v[72:73], off
	v_mul_f32_e32 v68, v68, v74
	v_mul_f32_e32 v64, v64, v68
	v_add_f32_e32 v68, 1.0, v75
	v_mul_f32_e32 v72, 0xbfb8aa3b, v70
	v_rcp_f32_e32 v68, v68
	v_exp_f32_e32 v72, v72
	v_mul_f32_e32 v73, 0xbfb8aa3b, v71
	v_exp_f32_e32 v73, v73
	v_mul_f32_e32 v68, v69, v68
	v_add_f32_e32 v69, 1.0, v72
	v_rcp_f32_e32 v69, v69
	v_add_f32_e32 v72, 1.0, v73
	v_rcp_f32_e32 v72, v72
	v_mul_f32_e32 v65, v65, v68
	v_mul_f32_e32 v68, v70, v69
	v_mul_f32_e32 v66, v66, v68
	v_mul_f32_e32 v68, v71, v72
	v_cvt_pk_bf16_f32 v64, v64, v65
	v_mul_f32_e32 v67, v67, v68
	v_cvt_pk_bf16_f32 v65, v66, v67
	global_store_dwordx2 v[80:81], v[64:65], off offset:128
	v_mul_f32_e32 v64, 0xbfb8aa3b, v60
	v_exp_f32_e32 v66, v64
	v_mul_f32_e32 v67, 0xbfb8aa3b, v61
	v_exp_f32_e32 v67, v67
	v_add_u32_e32 v64, 0x80, v150
	v_add_f32_e32 v66, 1.0, v66
	v_rcp_f32_e32 v66, v66
	v_mad_i64_i32 v[64:65], s[44:45], v64, s64, v[140:141]
	v_lshl_add_u64 v[64:65], v[64:65], 0, v[142:143]
	v_mul_f32_e32 v60, v60, v66
	v_mul_f32_e32 v56, v56, v60
	v_add_f32_e32 v60, 1.0, v67
	v_mul_f32_e32 v66, 0xbfb8aa3b, v62
	v_rcp_f32_e32 v60, v60
	v_exp_f32_e32 v66, v66
	v_mul_f32_e32 v67, 0xbfb8aa3b, v63
	v_exp_f32_e32 v67, v67
	v_mul_f32_e32 v60, v61, v60
	v_add_f32_e32 v61, 1.0, v66
	v_rcp_f32_e32 v61, v61
	v_add_f32_e32 v66, 1.0, v67
	v_rcp_f32_e32 v66, v66
	v_mul_f32_e32 v57, v57, v60
	v_mul_f32_e32 v60, v62, v61
	v_mul_f32_e32 v61, 0xbfb8aa3b, v52
	v_exp_f32_e32 v61, v61
	v_mul_f32_e32 v58, v58, v60
	v_mul_f32_e32 v60, v63, v66
	v_mul_f32_e32 v59, v59, v60
	v_cvt_pk_bf16_f32 v56, v56, v57
	v_cvt_pk_bf16_f32 v57, v58, v59
	v_add_f32_e32 v58, 1.0, v61
	v_rcp_f32_e32 v58, v58
	v_mul_f32_e32 v59, 0xbfb8aa3b, v53
	v_exp_f32_e32 v59, v59
	global_store_dwordx2 v[64:65], v[56:57], off
	v_mul_f32_e32 v52, v52, v58
	v_mul_f32_e32 v48, v48, v52
	v_add_f32_e32 v52, 1.0, v59
	v_mul_f32_e32 v56, 0xbfb8aa3b, v54
	v_rcp_f32_e32 v52, v52
	v_exp_f32_e32 v56, v56
	v_mul_f32_e32 v57, 0xbfb8aa3b, v55
	v_exp_f32_e32 v57, v57
	v_mul_f32_e32 v52, v53, v52
	v_add_f32_e32 v53, 1.0, v56
	v_rcp_f32_e32 v53, v53
	v_add_f32_e32 v56, 1.0, v57
	v_rcp_f32_e32 v56, v56
	v_mul_f32_e32 v49, v49, v52
	v_mul_f32_e32 v52, v54, v53
	v_mul_f32_e32 v50, v50, v52
	v_mul_f32_e32 v52, v55, v56
	v_cvt_pk_bf16_f32 v48, v48, v49
	v_mul_f32_e32 v51, v51, v52
	v_cvt_pk_bf16_f32 v49, v50, v51
	global_store_dwordx2 v[64:65], v[48:49], off offset:128
	v_mul_f32_e32 v48, 0xbfb8aa3b, v44
	v_exp_f32_e32 v50, v48
	v_mul_f32_e32 v51, 0xbfb8aa3b, v45
	v_exp_f32_e32 v51, v51
	v_add_u32_e32 v48, 0x90, v150
	v_add_f32_e32 v50, 1.0, v50
	v_rcp_f32_e32 v50, v50
	v_mad_i64_i32 v[48:49], s[44:45], v48, s64, v[140:141]
	v_lshl_add_u64 v[48:49], v[48:49], 0, v[142:143]
	v_mul_f32_e32 v44, v44, v50
	v_mul_f32_e32 v40, v40, v44
	v_add_f32_e32 v44, 1.0, v51
	v_mul_f32_e32 v50, 0xbfb8aa3b, v46
	v_rcp_f32_e32 v44, v44
	v_exp_f32_e32 v50, v50
	v_mul_f32_e32 v51, 0xbfb8aa3b, v47
	v_exp_f32_e32 v51, v51
	v_mul_f32_e32 v44, v45, v44
	v_add_f32_e32 v45, 1.0, v50
	v_rcp_f32_e32 v45, v45
	v_add_f32_e32 v50, 1.0, v51
	v_rcp_f32_e32 v50, v50
	v_mul_f32_e32 v41, v41, v44
	v_mul_f32_e32 v44, v46, v45
	v_mul_f32_e32 v45, 0xbfb8aa3b, v36
	v_exp_f32_e32 v45, v45
	v_mul_f32_e32 v42, v42, v44
	v_mul_f32_e32 v44, v47, v50
	v_mul_f32_e32 v43, v43, v44
	v_cvt_pk_bf16_f32 v40, v40, v41
	v_cvt_pk_bf16_f32 v41, v42, v43
	v_add_f32_e32 v42, 1.0, v45
	v_rcp_f32_e32 v42, v42
	v_mul_f32_e32 v43, 0xbfb8aa3b, v37
	v_exp_f32_e32 v43, v43
	global_store_dwordx2 v[48:49], v[40:41], off
	v_mul_f32_e32 v36, v36, v42
	v_mul_f32_e32 v32, v32, v36
	v_add_f32_e32 v36, 1.0, v43
	v_mul_f32_e32 v40, 0xbfb8aa3b, v38
	v_rcp_f32_e32 v36, v36
	v_exp_f32_e32 v40, v40
	v_mul_f32_e32 v41, 0xbfb8aa3b, v39
	v_exp_f32_e32 v41, v41
	v_mul_f32_e32 v36, v37, v36
	v_add_f32_e32 v37, 1.0, v40
	v_rcp_f32_e32 v37, v37
	v_add_f32_e32 v40, 1.0, v41
	v_rcp_f32_e32 v40, v40
	v_mul_f32_e32 v33, v33, v36
	v_mul_f32_e32 v36, v38, v37
	v_mul_f32_e32 v34, v34, v36
	v_mul_f32_e32 v36, v39, v40
	v_cvt_pk_bf16_f32 v32, v32, v33
	v_mul_f32_e32 v35, v35, v36
	v_cvt_pk_bf16_f32 v33, v34, v35
	global_store_dwordx2 v[48:49], v[32:33], off offset:128
	v_mul_f32_e32 v32, 0xbfb8aa3b, v28
	v_exp_f32_e32 v34, v32
	v_mul_f32_e32 v35, 0xbfb8aa3b, v29
	v_exp_f32_e32 v35, v35
	v_add_u32_e32 v32, 0xa0, v150
	v_add_f32_e32 v34, 1.0, v34
	v_rcp_f32_e32 v34, v34
	v_mad_i64_i32 v[32:33], s[44:45], v32, s64, v[140:141]
	v_lshl_add_u64 v[32:33], v[32:33], 0, v[142:143]
	v_mul_f32_e32 v28, v28, v34
	v_mul_f32_e32 v24, v24, v28
	v_add_f32_e32 v28, 1.0, v35
	v_mul_f32_e32 v34, 0xbfb8aa3b, v30
	v_rcp_f32_e32 v28, v28
	v_exp_f32_e32 v34, v34
	v_mul_f32_e32 v35, 0xbfb8aa3b, v31
	v_exp_f32_e32 v35, v35
	v_mul_f32_e32 v28, v29, v28
	v_add_f32_e32 v29, 1.0, v34
	v_rcp_f32_e32 v29, v29
	v_add_f32_e32 v34, 1.0, v35
	v_rcp_f32_e32 v34, v34
	v_mul_f32_e32 v25, v25, v28
	v_mul_f32_e32 v28, v30, v29
	v_mul_f32_e32 v29, 0xbfb8aa3b, v20
	v_exp_f32_e32 v29, v29
	v_mul_f32_e32 v26, v26, v28
	v_mul_f32_e32 v28, v31, v34
	v_mul_f32_e32 v27, v27, v28
	v_cvt_pk_bf16_f32 v24, v24, v25
	v_cvt_pk_bf16_f32 v25, v26, v27
	v_add_f32_e32 v26, 1.0, v29
	v_rcp_f32_e32 v26, v26
	v_mul_f32_e32 v27, 0xbfb8aa3b, v21
	v_exp_f32_e32 v27, v27
	global_store_dwordx2 v[32:33], v[24:25], off
	v_mul_f32_e32 v20, v20, v26
	v_mul_f32_e32 v16, v16, v20
	v_add_f32_e32 v20, 1.0, v27
	v_mul_f32_e32 v24, 0xbfb8aa3b, v22
	v_rcp_f32_e32 v20, v20
	v_exp_f32_e32 v24, v24
	v_mul_f32_e32 v25, 0xbfb8aa3b, v23
	v_exp_f32_e32 v25, v25
	v_mul_f32_e32 v20, v21, v20
	v_add_f32_e32 v21, 1.0, v24
	v_rcp_f32_e32 v21, v21
	v_add_f32_e32 v24, 1.0, v25
	v_rcp_f32_e32 v24, v24
	v_mul_f32_e32 v17, v17, v20
	v_mul_f32_e32 v20, v22, v21
	v_mul_f32_e32 v18, v18, v20
	v_mul_f32_e32 v20, v23, v24
	v_cvt_pk_bf16_f32 v16, v16, v17
	v_mul_f32_e32 v19, v19, v20
	v_cvt_pk_bf16_f32 v17, v18, v19
	global_store_dwordx2 v[32:33], v[16:17], off offset:128
	v_mul_f32_e32 v16, 0xbfb8aa3b, v12
	v_exp_f32_e32 v18, v16
	v_mul_f32_e32 v19, 0xbfb8aa3b, v13
	v_exp_f32_e32 v19, v19
	v_add_u32_e32 v16, 0xb0, v150
	v_add_f32_e32 v18, 1.0, v18
	v_rcp_f32_e32 v18, v18
	v_mad_i64_i32 v[16:17], s[44:45], v16, s64, v[140:141]
	v_lshl_add_u64 v[16:17], v[16:17], 0, v[142:143]
	v_mul_f32_e32 v12, v12, v18
	v_mul_f32_e32 v8, v8, v12
	v_add_f32_e32 v12, 1.0, v19
	v_mul_f32_e32 v18, 0xbfb8aa3b, v14
	v_rcp_f32_e32 v12, v12
	v_exp_f32_e32 v18, v18
	v_mul_f32_e32 v19, 0xbfb8aa3b, v15
	v_exp_f32_e32 v19, v19
	v_mul_f32_e32 v12, v13, v12
	v_add_f32_e32 v13, 1.0, v18
	v_rcp_f32_e32 v13, v13
	v_add_f32_e32 v18, 1.0, v19
	v_rcp_f32_e32 v18, v18
	v_mul_f32_e32 v9, v9, v12
	v_mul_f32_e32 v12, v14, v13
	v_mul_f32_e32 v13, 0xbfb8aa3b, v4
	v_exp_f32_e32 v13, v13
	v_mul_f32_e32 v10, v10, v12
	v_mul_f32_e32 v12, v15, v18
	v_mul_f32_e32 v11, v11, v12
	v_cvt_pk_bf16_f32 v8, v8, v9
	v_cvt_pk_bf16_f32 v9, v10, v11
	v_add_f32_e32 v10, 1.0, v13
	v_rcp_f32_e32 v10, v10
	v_mul_f32_e32 v11, 0xbfb8aa3b, v5
	v_exp_f32_e32 v11, v11
	global_store_dwordx2 v[16:17], v[8:9], off
	v_mul_f32_e32 v4, v4, v10
	v_mul_f32_e32 v0, v0, v4
	v_add_f32_e32 v4, 1.0, v11
	v_mul_f32_e32 v8, 0xbfb8aa3b, v6
	v_rcp_f32_e32 v4, v4
	v_exp_f32_e32 v8, v8
	v_mul_f32_e32 v9, 0xbfb8aa3b, v7
	v_exp_f32_e32 v9, v9
	v_mul_f32_e32 v4, v5, v4
	v_add_f32_e32 v5, 1.0, v8
	v_rcp_f32_e32 v5, v5
	v_add_f32_e32 v8, 1.0, v9
	v_rcp_f32_e32 v8, v8
	v_mul_f32_e32 v1, v1, v4
	v_mul_f32_e32 v4, v6, v5
	v_mul_f32_e32 v2, v2, v4
	v_mul_f32_e32 v4, v7, v8
	s_andn2_b64 vcc, exec, s[4:5]
	s_mov_b64 s[4:5], -1
	v_mul_f32_e32 v3, v3, v4
	v_cvt_pk_bf16_f32 v0, v0, v1
	v_cvt_pk_bf16_f32 v1, v2, v3
	global_store_dwordx2 v[16:17], v[0:1], off offset:128
	s_cbranch_vccnz .LBB0_180
	s_andn2_b64 vcc, exec, s[0:1]
	s_cbranch_vccnz .LBB0_179
	s_barrier
	s_branch .LBB0_179

.LBB0_267:
	v_lshl_add_u32 v152, s82, 8, v146
	v_lshl_or_b32 v144, s83, 8, v148
	v_ashrrev_i32_e32 v145, 31, v144
	v_ashrrev_i32_e32 v153, 31, v152
	v_lshl_add_u64 v[154:155], v[144:145], 1, s[24:25]
	v_lshlrev_b64 v[144:145], 11, v[152:153]
	v_lshl_add_u64 v[144:145], v[154:155], 0, v[144:145]
	s_nop 15
	s_nop 7
	v_cvt_pk_bf16_f32 v124, v124, v125
	v_cvt_pk_bf16_f32 v125, v126, v127
	v_cvt_pk_bf16_f32 v126, v120, v121
	v_cvt_pk_bf16_f32 v127, v122, v123
	global_store_dwordx4 v[144:145], v[124:127], off
	v_cvt_pk_bf16_f32 v112, v112, v113
	v_cvt_pk_bf16_f32 v113, v114, v115
	v_cvt_pk_bf16_f32 v114, v104, v105
	v_or_b32_e32 v104, 16, v152
	v_ashrrev_i32_e32 v105, 31, v104
	v_lshlrev_b64 v[104:105], 11, v[104:105]
	v_cvt_pk_bf16_f32 v115, v106, v107
	global_store_dwordx4 v[144:145], v[112:115], off offset:256
	s_nop 1
	v_lshl_add_u64 v[112:113], v[154:155], 0, v[104:105]
	v_cvt_pk_bf16_f32 v104, v116, v117
	v_cvt_pk_bf16_f32 v105, v118, v119
	v_cvt_pk_bf16_f32 v106, v108, v109
	v_cvt_pk_bf16_f32 v107, v110, v111
	global_store_dwordx4 v[112:113], v[104:107], off
	v_cvt_pk_bf16_f32 v96, v96, v97
	v_cvt_pk_bf16_f32 v97, v98, v99
	v_cvt_pk_bf16_f32 v98, v88, v89
	v_or_b32_e32 v88, 32, v152
	v_ashrrev_i32_e32 v89, 31, v88
	v_lshlrev_b64 v[88:89], 11, v[88:89]
	v_cvt_pk_bf16_f32 v99, v90, v91
	global_store_dwordx4 v[112:113], v[96:99], off offset:256
	s_nop 1
	v_lshl_add_u64 v[96:97], v[154:155], 0, v[88:89]
	v_cvt_pk_bf16_f32 v88, v100, v101
	v_cvt_pk_bf16_f32 v89, v102, v103
	v_cvt_pk_bf16_f32 v90, v92, v93
	v_cvt_pk_bf16_f32 v91, v94, v95
	global_store_dwordx4 v[96:97], v[88:91], off
	v_cvt_pk_bf16_f32 v80, v80, v81
	v_cvt_pk_bf16_f32 v81, v82, v83
	v_cvt_pk_bf16_f32 v82, v72, v73
	v_or_b32_e32 v72, 48, v152
	s_and_b64 vcc, exec, s[10:11]
	s_cbranch_vccz .Lxb_1
	s_barrier
.Lxb_1:
	v_ashrrev_i32_e32 v73, 31, v72
	v_lshlrev_b64 v[72:73], 11, v[72:73]
	v_cvt_pk_bf16_f32 v83, v74, v75
	global_store_dwordx4 v[96:97], v[80:83], off offset:256
	s_nop 1
	v_lshl_add_u64 v[80:81], v[154:155], 0, v[72:73]
	v_cvt_pk_bf16_f32 v72, v84, v85
	v_cvt_pk_bf16_f32 v73, v86, v87
	v_cvt_pk_bf16_f32 v74, v76, v77
	v_cvt_pk_bf16_f32 v75, v78, v79
	global_store_dwordx4 v[80:81], v[72:75], off
	v_cvt_pk_bf16_f32 v68, v68, v69
	v_cvt_pk_bf16_f32 v69, v70, v71
	v_cvt_pk_bf16_f32 v70, v64, v65
	v_cvt_pk_bf16_f32 v71, v66, v67
	global_store_dwordx4 v[80:81], v[68:71], off offset:256
	v_cvt_pk_bf16_f32 v60, v60, v61
	v_cvt_pk_bf16_f32 v61, v62, v63
	v_cvt_pk_bf16_f32 v62, v56, v57
	v_add_co_u32_e32 v56, vcc, s72, v144
	v_lshl_add_u64 v[64:65], v[144:145], 0, s[30:31]
	s_nop 0
	v_addc_co_u32_e32 v57, vcc, 0, v145, vcc
	v_cvt_pk_bf16_f32 v63, v58, v59
	global_store_dwordx4 v[56:57], v[60:63], off
	v_cvt_pk_bf16_f32 v48, v48, v49
	v_cvt_pk_bf16_f32 v49, v50, v51
	v_cvt_pk_bf16_f32 v50, v40, v41
	v_cvt_pk_bf16_f32 v51, v42, v43
	global_store_dwordx4 v[64:65], v[48:51], off offset:256
	v_cvt_pk_bf16_f32 v40, v52, v53
	v_cvt_pk_bf16_f32 v41, v54, v55
	v_cvt_pk_bf16_f32 v42, v44, v45
	v_add_co_u32_e32 v44, vcc, s73, v144
	s_nop 0
	v_lshl_add_u64 v[48:49], v[144:145], 0, s[36:37]
	v_addc_co_u32_e32 v45, vcc, 0, v145, vcc
	v_cvt_pk_bf16_f32 v43, v46, v47
	global_store_dwordx4 v[44:45], v[40:43], off
	v_cvt_pk_bf16_f32 v32, v32, v33
	v_cvt_pk_bf16_f32 v33, v34, v35
	v_cvt_pk_bf16_f32 v34, v24, v25
	v_cvt_pk_bf16_f32 v35, v26, v27
	global_store_dwordx4 v[48:49], v[32:35], off offset:256
	v_cvt_pk_bf16_f32 v24, v36, v37
	v_cvt_pk_bf16_f32 v25, v38, v39
	v_cvt_pk_bf16_f32 v26, v28, v29
	v_add_co_u32_e32 v28, vcc, s74, v144
	s_nop 0
	v_lshl_add_u64 v[32:33], v[144:145], 0, s[44:45]
	v_addc_co_u32_e32 v29, vcc, 0, v145, vcc
	v_cvt_pk_bf16_f32 v27, v30, v31
	global_store_dwordx4 v[28:29], v[24:27], off
	v_cvt_pk_bf16_f32 v16, v16, v17
	v_cvt_pk_bf16_f32 v17, v18, v19
	v_cvt_pk_bf16_f32 v18, v8, v9
	v_cvt_pk_bf16_f32 v19, v10, v11
	global_store_dwordx4 v[32:33], v[16:19], off offset:256
	v_cvt_pk_bf16_f32 v8, v20, v21
	v_cvt_pk_bf16_f32 v9, v22, v23
	v_cvt_pk_bf16_f32 v10, v12, v13
	v_add_co_u32_e32 v12, vcc, s75, v144
	s_nop 0
	v_lshl_add_u64 v[16:17], v[144:145], 0, s[46:47]
	v_addc_co_u32_e32 v13, vcc, 0, v145, vcc
	s_and_b64 vcc, exec, s[4:5]
	s_mov_b64 s[4:5], -1
	v_cvt_pk_bf16_f32 v11, v14, v15
	global_store_dwordx4 v[12:13], v[8:11], off
	v_cvt_pk_bf16_f32 v4, v4, v5
	v_cvt_pk_bf16_f32 v5, v6, v7
	v_cvt_pk_bf16_f32 v6, v0, v1
	v_cvt_pk_bf16_f32 v7, v2, v3
	global_store_dwordx4 v[16:17], v[4:7], off offset:256
	s_cbranch_vccnz .LBB0_252
	s_andn2_b64 vcc, exec, s[0:1]
	s_cbranch_vccnz .LBB0_251
	s_barrier
	s_branch .LBB0_251

.LBB0_390:
	s_lshl_b32 s18, s57, 8
	s_or_b32 s18, s18, s73
	v_lshl_add_u32 v152, s56, 8, v146
	s_ashr_i32 s56, s18, 6
	s_ashr_i32 s57, s56, 31
	s_lshl_b64 s[58:59], s[56:57], 22
	s_cmp_lt_i32 s56, 16
	s_cselect_b64 vcc, -1, 0
	v_cndmask_b32_e32 v156, 1.0, v151, vcc
	v_pk_mul_f32 v[124:125], v[156:157], v[124:125] op_sel_hi:[0,1]
	v_ashrrev_i32_e32 v153, 31, v152
	v_lshl_add_u64 v[154:155], v[136:137], 0, s[58:59]
	v_pk_mul_f32 v[126:127], v[156:157], v[126:127] op_sel_hi:[0,1]
	v_pk_mul_f32 v[158:159], v[156:157], v[122:123] op_sel_hi:[0,1]
	v_pk_mul_f32 v[122:123], v[156:157], v[120:121] op_sel_hi:[0,1]
	v_cvt_pk_bf16_f32 v120, v124, v125
	v_lshlrev_b64 v[124:125], 7, v[152:153]
	v_cvt_pk_bf16_f32 v121, v126, v127
	v_lshl_add_u64 v[126:127], v[154:155], 0, v[124:125]
	v_pk_mul_f32 v[116:117], v[156:157], v[116:117] op_sel_hi:[0,1]
	v_cvt_pk_bf16_f32 v122, v122, v123
	v_cvt_pk_bf16_f32 v123, v158, v159
	global_store_dwordx4 v[126:127], v[120:123], off
	v_pk_mul_f32 v[118:119], v[156:157], v[118:119] op_sel_hi:[0,1]
	v_pk_mul_f32 v[108:109], v[156:157], v[108:109] op_sel_hi:[0,1]
	v_pk_mul_f32 v[120:121], v[156:157], v[114:115] op_sel_hi:[0,1]
	v_pk_mul_f32 v[114:115], v[156:157], v[112:113] op_sel_hi:[0,1]
	v_cvt_pk_bf16_f32 v112, v116, v117
	v_or_b32_e32 v116, 16, v152
	v_ashrrev_i32_e32 v117, 31, v116
	v_lshlrev_b64 v[116:117], 7, v[116:117]
	v_cvt_pk_bf16_f32 v113, v118, v119
	v_lshl_add_u64 v[118:119], v[154:155], 0, v[116:117]
	v_cvt_pk_bf16_f32 v114, v114, v115
	v_cvt_pk_bf16_f32 v115, v120, v121
	global_store_dwordx4 v[118:119], v[112:115], off
	v_pk_mul_f32 v[110:111], v[156:157], v[110:111] op_sel_hi:[0,1]
	v_pk_mul_f32 v[100:101], v[156:157], v[100:101] op_sel_hi:[0,1]
	v_pk_mul_f32 v[112:113], v[156:157], v[106:107] op_sel_hi:[0,1]
	v_pk_mul_f32 v[106:107], v[156:157], v[104:105] op_sel_hi:[0,1]
	v_cvt_pk_bf16_f32 v104, v108, v109
	v_or_b32_e32 v108, 32, v152
	v_ashrrev_i32_e32 v109, 31, v108
	v_lshlrev_b64 v[108:109], 7, v[108:109]
	v_cvt_pk_bf16_f32 v105, v110, v111
	v_lshl_add_u64 v[110:111], v[154:155], 0, v[108:109]
	v_cvt_pk_bf16_f32 v106, v106, v107
	v_cvt_pk_bf16_f32 v107, v112, v113
	s_and_b64 vcc, exec, s[8:9]
	s_cbranch_vccz .Lxb_2
	s_barrier
.Lxb_2:
	global_store_dwordx4 v[110:111], v[104:107], off
	v_pk_mul_f32 v[102:103], v[156:157], v[102:103] op_sel_hi:[0,1]
	v_pk_mul_f32 v[92:93], v[156:157], v[92:93] op_sel_hi:[0,1]
	v_pk_mul_f32 v[104:105], v[156:157], v[98:99] op_sel_hi:[0,1]
	v_pk_mul_f32 v[98:99], v[156:157], v[96:97] op_sel_hi:[0,1]
	v_cvt_pk_bf16_f32 v96, v100, v101
	v_or_b32_e32 v100, 48, v152
	v_ashrrev_i32_e32 v101, 31, v100
	v_lshlrev_b64 v[100:101], 7, v[100:101]
	v_cvt_pk_bf16_f32 v97, v102, v103
	v_lshl_add_u64 v[102:103], v[154:155], 0, v[100:101]
	v_cvt_pk_bf16_f32 v98, v98, v99
	v_cvt_pk_bf16_f32 v99, v104, v105
	global_store_dwordx4 v[102:103], v[96:99], off
	v_pk_mul_f32 v[94:95], v[156:157], v[94:95] op_sel_hi:[0,1]
	v_pk_mul_f32 v[84:85], v[156:157], v[84:85] op_sel_hi:[0,1]
	v_pk_mul_f32 v[96:97], v[156:157], v[90:91] op_sel_hi:[0,1]
	v_pk_mul_f32 v[90:91], v[156:157], v[88:89] op_sel_hi:[0,1]
	v_cvt_pk_bf16_f32 v88, v92, v93
	v_lshl_add_u64 v[92:93], v[124:125], 0, s[10:11]
	v_cvt_pk_bf16_f32 v89, v94, v95
	v_lshl_add_u64 v[94:95], v[154:155], 0, v[92:93]
	v_cvt_pk_bf16_f32 v90, v90, v91
	v_cvt_pk_bf16_f32 v91, v96, v97
	global_store_dwordx4 v[94:95], v[88:91], off
	v_pk_mul_f32 v[86:87], v[156:157], v[86:87] op_sel_hi:[0,1]
	s_or_b32 s56, s56, 2
	v_pk_mul_f32 v[88:89], v[156:157], v[82:83] op_sel_hi:[0,1]
	v_pk_mul_f32 v[82:83], v[156:157], v[80:81] op_sel_hi:[0,1]
	v_cvt_pk_bf16_f32 v80, v84, v85
	v_lshl_add_u64 v[84:85], v[124:125], 0, s[16:17]
	v_cvt_pk_bf16_f32 v81, v86, v87
	v_lshl_add_u64 v[86:87], v[154:155], 0, v[84:85]
	v_pk_mul_f32 v[76:77], v[156:157], v[76:77] op_sel_hi:[0,1]
	s_ashr_i32 s57, s56, 31
	v_cvt_pk_bf16_f32 v82, v82, v83
	v_cvt_pk_bf16_f32 v83, v88, v89
	global_store_dwordx4 v[86:87], v[80:83], off
	v_pk_mul_f32 v[78:79], v[156:157], v[78:79] op_sel_hi:[0,1]
	s_lshl_b64 s[58:59], s[56:57], 22
	v_pk_mul_f32 v[80:81], v[156:157], v[74:75] op_sel_hi:[0,1]
	v_pk_mul_f32 v[74:75], v[156:157], v[72:73] op_sel_hi:[0,1]
	v_cvt_pk_bf16_f32 v72, v76, v77
	v_lshl_add_u64 v[76:77], v[124:125], 0, s[36:37]
	v_cvt_pk_bf16_f32 v73, v78, v79
	v_lshl_add_u64 v[78:79], v[154:155], 0, v[76:77]
	v_pk_mul_f32 v[60:61], v[156:157], v[60:61] op_sel_hi:[0,1]
	s_cmp_lt_i32 s56, 16
	v_cvt_pk_bf16_f32 v74, v74, v75
	v_cvt_pk_bf16_f32 v75, v80, v81
	global_store_dwordx4 v[78:79], v[72:75], off
	v_pk_mul_f32 v[62:63], v[156:157], v[62:63] op_sel_hi:[0,1]
	s_cselect_b64 vcc, -1, 0
	v_pk_mul_f32 v[72:73], v[156:157], v[58:59] op_sel_hi:[0,1]
	v_pk_mul_f32 v[58:59], v[156:157], v[56:57] op_sel_hi:[0,1]
	v_cvt_pk_bf16_f32 v56, v60, v61
	v_lshl_add_u64 v[60:61], v[124:125], 0, s[44:45]
	v_cvt_pk_bf16_f32 v57, v62, v63
	v_cvt_pk_bf16_f32 v58, v58, v59
	v_cvt_pk_bf16_f32 v59, v72, v73
	v_lshl_add_u64 v[62:63], v[154:155], 0, v[60:61]
	v_cndmask_b32_e32 v72, 1.0, v151, vcc
	global_store_dwordx4 v[62:63], v[56:59], off
	v_lshl_add_u64 v[62:63], v[136:137], 0, s[58:59]
	v_pk_mul_f32 v[64:65], v[72:73], v[64:65] op_sel_hi:[0,1]
	v_pk_mul_f32 v[58:59], v[72:73], v[70:71] op_sel_hi:[0,1]
	v_pk_mul_f32 v[56:57], v[72:73], v[68:69] op_sel_hi:[0,1]
	v_cvt_pk_bf16_f32 v56, v56, v57
	v_cvt_pk_bf16_f32 v57, v58, v59
	v_cvt_pk_bf16_f32 v58, v64, v65
	v_lshl_add_u64 v[64:65], v[62:63], 0, v[124:125]
	v_pk_mul_f32 v[52:53], v[72:73], v[52:53] op_sel_hi:[0,1]
	v_pk_mul_f32 v[66:67], v[72:73], v[66:67] op_sel_hi:[0,1]
	v_cvt_pk_bf16_f32 v59, v66, v67
	global_store_dwordx4 v[64:65], v[56:59], off
	v_pk_mul_f32 v[54:55], v[72:73], v[54:55] op_sel_hi:[0,1]
	v_pk_mul_f32 v[44:45], v[72:73], v[44:45] op_sel_hi:[0,1]
	v_pk_mul_f32 v[56:57], v[72:73], v[50:51] op_sel_hi:[0,1]
	v_pk_mul_f32 v[50:51], v[72:73], v[48:49] op_sel_hi:[0,1]
	v_cvt_pk_bf16_f32 v48, v52, v53
	v_cvt_pk_bf16_f32 v49, v54, v55
	v_lshl_add_u64 v[52:53], v[62:63], 0, v[116:117]
	v_cvt_pk_bf16_f32 v50, v50, v51
	v_cvt_pk_bf16_f32 v51, v56, v57
	global_store_dwordx4 v[52:53], v[48:51], off
	v_pk_mul_f32 v[46:47], v[72:73], v[46:47] op_sel_hi:[0,1]
	v_pk_mul_f32 v[36:37], v[72:73], v[36:37] op_sel_hi:[0,1]
	v_pk_mul_f32 v[48:49], v[72:73], v[42:43] op_sel_hi:[0,1]
	v_pk_mul_f32 v[42:43], v[72:73], v[40:41] op_sel_hi:[0,1]
	v_cvt_pk_bf16_f32 v40, v44, v45
	v_cvt_pk_bf16_f32 v41, v46, v47
	v_lshl_add_u64 v[44:45], v[62:63], 0, v[108:109]
	v_cvt_pk_bf16_f32 v42, v42, v43
	v_cvt_pk_bf16_f32 v43, v48, v49
	global_store_dwordx4 v[44:45], v[40:43], off
	v_pk_mul_f32 v[38:39], v[72:73], v[38:39] op_sel_hi:[0,1]
	v_pk_mul_f32 v[28:29], v[72:73], v[28:29] op_sel_hi:[0,1]
	v_pk_mul_f32 v[40:41], v[72:73], v[34:35] op_sel_hi:[0,1]
	v_pk_mul_f32 v[34:35], v[72:73], v[32:33] op_sel_hi:[0,1]
	v_cvt_pk_bf16_f32 v32, v36, v37
	v_cvt_pk_bf16_f32 v33, v38, v39
	v_lshl_add_u64 v[36:37], v[62:63], 0, v[100:101]
	v_cvt_pk_bf16_f32 v34, v34, v35
	v_cvt_pk_bf16_f32 v35, v40, v41
	global_store_dwordx4 v[36:37], v[32:35], off
	v_pk_mul_f32 v[30:31], v[72:73], v[30:31] op_sel_hi:[0,1]
	v_pk_mul_f32 v[20:21], v[72:73], v[20:21] op_sel_hi:[0,1]
	v_pk_mul_f32 v[32:33], v[72:73], v[26:27] op_sel_hi:[0,1]
	v_pk_mul_f32 v[26:27], v[72:73], v[24:25] op_sel_hi:[0,1]
	v_cvt_pk_bf16_f32 v24, v28, v29
	v_cvt_pk_bf16_f32 v25, v30, v31
	v_lshl_add_u64 v[28:29], v[62:63], 0, v[92:93]
	v_cvt_pk_bf16_f32 v26, v26, v27
	v_cvt_pk_bf16_f32 v27, v32, v33
	global_store_dwordx4 v[28:29], v[24:27], off
	v_pk_mul_f32 v[22:23], v[72:73], v[22:23] op_sel_hi:[0,1]
	v_pk_mul_f32 v[12:13], v[72:73], v[12:13] op_sel_hi:[0,1]
	v_pk_mul_f32 v[24:25], v[72:73], v[18:19] op_sel_hi:[0,1]
	v_pk_mul_f32 v[18:19], v[72:73], v[16:17] op_sel_hi:[0,1]
	v_cvt_pk_bf16_f32 v16, v20, v21
	v_cvt_pk_bf16_f32 v17, v22, v23
	v_lshl_add_u64 v[20:21], v[62:63], 0, v[84:85]
	v_cvt_pk_bf16_f32 v18, v18, v19
	v_cvt_pk_bf16_f32 v19, v24, v25
	global_store_dwordx4 v[20:21], v[16:19], off
	v_pk_mul_f32 v[14:15], v[72:73], v[14:15] op_sel_hi:[0,1]
	v_pk_mul_f32 v[4:5], v[72:73], v[4:5] op_sel_hi:[0,1]
	v_pk_mul_f32 v[16:17], v[72:73], v[10:11] op_sel_hi:[0,1]
	v_pk_mul_f32 v[10:11], v[72:73], v[8:9] op_sel_hi:[0,1]
	v_cvt_pk_bf16_f32 v8, v12, v13
	v_cvt_pk_bf16_f32 v9, v14, v15
	v_lshl_add_u64 v[12:13], v[62:63], 0, v[76:77]
	v_cvt_pk_bf16_f32 v10, v10, v11
	v_cvt_pk_bf16_f32 v11, v16, v17
	global_store_dwordx4 v[12:13], v[8:11], off
	s_andn2_b64 vcc, exec, s[4:5]
	s_mov_b64 s[4:5], -1
	v_pk_mul_f32 v[8:9], v[72:73], v[2:3] op_sel_hi:[0,1]
	v_pk_mul_f32 v[2:3], v[72:73], v[0:1] op_sel_hi:[0,1]
	v_cvt_pk_bf16_f32 v0, v4, v5
	v_lshl_add_u64 v[4:5], v[62:63], 0, v[60:61]
	v_pk_mul_f32 v[6:7], v[72:73], v[6:7] op_sel_hi:[0,1]
	v_cvt_pk_bf16_f32 v1, v6, v7
	v_cvt_pk_bf16_f32 v2, v2, v3
	v_cvt_pk_bf16_f32 v3, v8, v9
	global_store_dwordx4 v[4:5], v[0:3], off
	s_cbranch_vccnz .LBB0_383
	s_andn2_b64 vcc, exec, s[0:1]
	s_cbranch_vccnz .LBB0_382
	s_barrier
	s_branch .LBB0_382

.LBB0_604:
	v_lshl_add_u32 v152, s56, 8, v146
	v_lshl_or_b32 v144, s83, 8, v148
	v_ashrrev_i32_e32 v145, 31, v144
	v_ashrrev_i32_e32 v153, 31, v152
	v_lshl_add_u64 v[154:155], v[144:145], 1, s[24:25]
	v_lshlrev_b64 v[144:145], 11, v[152:153]
	v_lshl_add_u64 v[144:145], v[154:155], 0, v[144:145]
	s_nop 15
	s_nop 7
	v_cvt_pk_bf16_f32 v124, v124, v125
	v_cvt_pk_bf16_f32 v125, v126, v127
	v_cvt_pk_bf16_f32 v126, v120, v121
	v_cvt_pk_bf16_f32 v127, v122, v123
	global_store_dwordx4 v[144:145], v[124:127], off
	v_cvt_pk_bf16_f32 v112, v112, v113
	v_cvt_pk_bf16_f32 v113, v114, v115
	v_cvt_pk_bf16_f32 v114, v104, v105
	v_or_b32_e32 v104, 16, v152
	v_ashrrev_i32_e32 v105, 31, v104
	v_lshlrev_b64 v[104:105], 11, v[104:105]
	v_cvt_pk_bf16_f32 v115, v106, v107
	global_store_dwordx4 v[144:145], v[112:115], off offset:256
	s_nop 1
	v_lshl_add_u64 v[112:113], v[154:155], 0, v[104:105]
	v_cvt_pk_bf16_f32 v104, v116, v117
	v_cvt_pk_bf16_f32 v105, v118, v119
	v_cvt_pk_bf16_f32 v106, v108, v109
	v_cvt_pk_bf16_f32 v107, v110, v111
	global_store_dwordx4 v[112:113], v[104:107], off
	v_cvt_pk_bf16_f32 v96, v96, v97
	v_cvt_pk_bf16_f32 v97, v98, v99
	v_cvt_pk_bf16_f32 v98, v88, v89
	v_or_b32_e32 v88, 32, v152
	v_ashrrev_i32_e32 v89, 31, v88
	v_lshlrev_b64 v[88:89], 11, v[88:89]
	v_cvt_pk_bf16_f32 v99, v90, v91
	global_store_dwordx4 v[112:113], v[96:99], off offset:256
	s_nop 1
	v_lshl_add_u64 v[96:97], v[154:155], 0, v[88:89]
	v_cvt_pk_bf16_f32 v88, v100, v101
	v_cvt_pk_bf16_f32 v89, v102, v103
	v_cvt_pk_bf16_f32 v90, v92, v93
	v_cvt_pk_bf16_f32 v91, v94, v95
	global_store_dwordx4 v[96:97], v[88:91], off
	v_cvt_pk_bf16_f32 v80, v80, v81
	v_cvt_pk_bf16_f32 v81, v82, v83
	v_cvt_pk_bf16_f32 v82, v72, v73
	v_or_b32_e32 v72, 48, v152
	s_and_b64 vcc, exec, s[12:13]
	s_cbranch_vccz .Lxb_3
	s_barrier
.Lxb_3:
	v_ashrrev_i32_e32 v73, 31, v72
	v_lshlrev_b64 v[72:73], 11, v[72:73]
	v_cvt_pk_bf16_f32 v83, v74, v75
	global_store_dwordx4 v[96:97], v[80:83], off offset:256
	s_nop 1
	v_lshl_add_u64 v[80:81], v[154:155], 0, v[72:73]
	v_cvt_pk_bf16_f32 v72, v84, v85
	v_cvt_pk_bf16_f32 v73, v86, v87
	v_cvt_pk_bf16_f32 v74, v76, v77
	v_cvt_pk_bf16_f32 v75, v78, v79
	global_store_dwordx4 v[80:81], v[72:75], off
	v_cvt_pk_bf16_f32 v68, v68, v69
	v_cvt_pk_bf16_f32 v69, v70, v71
	v_cvt_pk_bf16_f32 v70, v64, v65
	v_cvt_pk_bf16_f32 v71, v66, v67
	global_store_dwordx4 v[80:81], v[68:71], off offset:256
	v_cvt_pk_bf16_f32 v60, v60, v61
	v_cvt_pk_bf16_f32 v61, v62, v63
	v_cvt_pk_bf16_f32 v62, v56, v57
	v_add_co_u32_e32 v56, vcc, s75, v144
	v_lshl_add_u64 v[64:65], v[144:145], 0, s[0:1]
	s_nop 0
	v_addc_co_u32_e32 v57, vcc, 0, v145, vcc
	v_cvt_pk_bf16_f32 v63, v58, v59
	global_store_dwordx4 v[56:57], v[60:63], off
	v_cvt_pk_bf16_f32 v48, v48, v49
	v_cvt_pk_bf16_f32 v49, v50, v51
	v_cvt_pk_bf16_f32 v50, v40, v41
	v_cvt_pk_bf16_f32 v51, v42, v43
	global_store_dwordx4 v[64:65], v[48:51], off offset:256
	v_cvt_pk_bf16_f32 v40, v52, v53
	v_cvt_pk_bf16_f32 v41, v54, v55
	v_cvt_pk_bf16_f32 v42, v44, v45
	v_add_co_u32_e32 v44, vcc, s76, v144
	s_nop 0
	v_lshl_add_u64 v[48:49], v[144:145], 0, s[16:17]
	v_addc_co_u32_e32 v45, vcc, 0, v145, vcc
	v_cvt_pk_bf16_f32 v43, v46, v47
	global_store_dwordx4 v[44:45], v[40:43], off
	v_cvt_pk_bf16_f32 v32, v32, v33
	v_cvt_pk_bf16_f32 v33, v34, v35
	v_cvt_pk_bf16_f32 v34, v24, v25
	v_cvt_pk_bf16_f32 v35, v26, v27
	global_store_dwordx4 v[48:49], v[32:35], off offset:256
	v_cvt_pk_bf16_f32 v24, v36, v37
	v_cvt_pk_bf16_f32 v25, v38, v39
	v_cvt_pk_bf16_f32 v26, v28, v29
	v_add_co_u32_e32 v28, vcc, s77, v144
	s_nop 0
	v_lshl_add_u64 v[32:33], v[144:145], 0, s[36:37]
	v_addc_co_u32_e32 v29, vcc, 0, v145, vcc
	v_cvt_pk_bf16_f32 v27, v30, v31
	global_store_dwordx4 v[28:29], v[24:27], off
	v_cvt_pk_bf16_f32 v16, v16, v17
	v_cvt_pk_bf16_f32 v17, v18, v19
	v_cvt_pk_bf16_f32 v18, v8, v9
	v_cvt_pk_bf16_f32 v19, v10, v11
	global_store_dwordx4 v[32:33], v[16:19], off offset:256
	v_cvt_pk_bf16_f32 v8, v20, v21
	v_cvt_pk_bf16_f32 v9, v22, v23
	v_cvt_pk_bf16_f32 v10, v12, v13
	v_add_co_u32_e32 v12, vcc, s82, v144
	s_nop 0
	v_lshl_add_u64 v[16:17], v[144:145], 0, s[44:45]
	v_addc_co_u32_e32 v13, vcc, 0, v145, vcc
	s_andn2_b64 vcc, exec, s[4:5]
	s_mov_b64 s[4:5], -1
	v_cvt_pk_bf16_f32 v11, v14, v15
	global_store_dwordx4 v[12:13], v[8:11], off
	v_cvt_pk_bf16_f32 v4, v4, v5
	v_cvt_pk_bf16_f32 v5, v6, v7
	v_cvt_pk_bf16_f32 v6, v0, v1
	v_cvt_pk_bf16_f32 v7, v2, v3
	global_store_dwordx4 v[16:17], v[4:7], off offset:256
	s_cbranch_vccnz .LBB0_593
	s_andn2_b64 vcc, exec, s[8:9]
	s_cbranch_vccnz .LBB0_592
	s_barrier
	s_branch .LBB0_592

.LBB0_727:
	v_mul_f32_e32 v151, 0xbfb8aa3b, v124
	v_exp_f32_e32 v151, v151
	v_mul_f32_e32 v154, 0xbfb8aa3b, v125
	v_exp_f32_e32 v154, v154
	v_lshl_or_b32 v142, s69, 7, v146
	v_add_f32_e32 v151, 1.0, v151
	v_rcp_f32_e32 v151, v151
	v_lshl_add_u32 v150, s46, 8, v144
	v_ashrrev_i32_e32 v143, 31, v142
	v_mov_b64_e32 v[140:141], s[22:23]
	v_mul_f32_e32 v124, v124, v151
	v_mul_f32_e32 v120, v120, v124
	v_add_f32_e32 v124, 1.0, v154
	v_mul_f32_e32 v151, 0xbfb8aa3b, v126
	v_rcp_f32_e32 v124, v124
	v_exp_f32_e32 v151, v151
	v_mul_f32_e32 v154, 0xbfb8aa3b, v127
	v_exp_f32_e32 v154, v154
	v_mul_f32_e32 v124, v125, v124
	v_add_f32_e32 v125, 1.0, v151
	v_rcp_f32_e32 v125, v125
	v_add_f32_e32 v151, 1.0, v154
	v_rcp_f32_e32 v151, v151
	v_mul_f32_e32 v121, v121, v124
	v_mul_f32_e32 v124, v126, v125
	v_mul_f32_e32 v125, 0xbfb8aa3b, v116
	v_exp_f32_e32 v125, v125
	v_mul_f32_e32 v122, v122, v124
	v_mul_f32_e32 v124, v127, v151
	v_mul_f32_e32 v123, v123, v124
	v_cvt_pk_bf16_f32 v120, v120, v121
	v_cvt_pk_bf16_f32 v121, v122, v123
	v_add_f32_e32 v122, 1.0, v125
	v_rcp_f32_e32 v122, v122
	v_mul_f32_e32 v123, 0xbfb8aa3b, v117
	v_exp_f32_e32 v123, v123
	v_mad_i64_i32 v[152:153], s[48:49], v150, s68, v[140:141]
	v_lshlrev_b64 v[142:143], 1, v[142:143]
	v_lshl_add_u64 v[152:153], v[152:153], 0, v[142:143]
	v_mul_f32_e32 v116, v116, v122
	global_store_dwordx2 v[152:153], v[120:121], off
	v_mul_f32_e32 v112, v112, v116
	v_add_f32_e32 v116, 1.0, v123
	v_mul_f32_e32 v120, 0xbfb8aa3b, v118
	v_rcp_f32_e32 v116, v116
	v_exp_f32_e32 v120, v120
	v_mul_f32_e32 v121, 0xbfb8aa3b, v119
	v_exp_f32_e32 v121, v121
	v_mul_f32_e32 v116, v117, v116
	v_add_f32_e32 v117, 1.0, v120
	v_rcp_f32_e32 v117, v117
	v_add_f32_e32 v120, 1.0, v121
	v_rcp_f32_e32 v120, v120
	v_mul_f32_e32 v113, v113, v116
	v_mul_f32_e32 v116, v118, v117
	v_mul_f32_e32 v114, v114, v116
	v_mul_f32_e32 v116, v119, v120
	v_cvt_pk_bf16_f32 v112, v112, v113
	v_mul_f32_e32 v115, v115, v116
	v_cvt_pk_bf16_f32 v113, v114, v115
	global_store_dwordx2 v[152:153], v[112:113], off offset:128
	v_mul_f32_e32 v112, 0xbfb8aa3b, v108
	v_exp_f32_e32 v114, v112
	v_mul_f32_e32 v115, 0xbfb8aa3b, v109
	s_and_b64 vcc, exec, s[16:17]
	s_cbranch_vccz .Lxb_4
	s_barrier
.Lxb_4:
	v_exp_f32_e32 v115, v115
	v_or_b32_e32 v112, 16, v150
	v_add_f32_e32 v114, 1.0, v114
	v_rcp_f32_e32 v114, v114
	v_mad_i64_i32 v[112:113], s[48:49], v112, s68, v[140:141]
	v_lshl_add_u64 v[112:113], v[112:113], 0, v[142:143]
	v_mul_f32_e32 v108, v108, v114
	v_mul_f32_e32 v104, v104, v108
	v_add_f32_e32 v108, 1.0, v115
	v_mul_f32_e32 v114, 0xbfb8aa3b, v110
	v_rcp_f32_e32 v108, v108
	v_exp_f32_e32 v114, v114
	v_mul_f32_e32 v115, 0xbfb8aa3b, v111
	v_exp_f32_e32 v115, v115
	v_mul_f32_e32 v108, v109, v108
	v_add_f32_e32 v109, 1.0, v114
	v_rcp_f32_e32 v109, v109
	v_add_f32_e32 v114, 1.0, v115
	v_rcp_f32_e32 v114, v114
	v_mul_f32_e32 v105, v105, v108
	v_mul_f32_e32 v108, v110, v109
	v_mul_f32_e32 v109, 0xbfb8aa3b, v100
	v_exp_f32_e32 v109, v109
	v_mul_f32_e32 v106, v106, v108
	v_mul_f32_e32 v108, v111, v114
	v_mul_f32_e32 v107, v107, v108
	v_cvt_pk_bf16_f32 v104, v104, v105
	v_cvt_pk_bf16_f32 v105, v106, v107
	v_add_f32_e32 v106, 1.0, v109
	v_rcp_f32_e32 v106, v106
	v_mul_f32_e32 v107, 0xbfb8aa3b, v101
	v_exp_f32_e32 v107, v107
	global_store_dwordx2 v[112:113], v[104:105], off
	v_mul_f32_e32 v100, v100, v106
	v_mul_f32_e32 v96, v96, v100
	v_add_f32_e32 v100, 1.0, v107
	v_mul_f32_e32 v104, 0xbfb8aa3b, v102
	v_rcp_f32_e32 v100, v100
	v_exp_f32_e32 v104, v104
	v_mul_f32_e32 v105, 0xbfb8aa3b, v103
	v_exp_f32_e32 v105, v105
	v_mul_f32_e32 v100, v101, v100
	v_add_f32_e32 v101, 1.0, v104
	v_rcp_f32_e32 v101, v101
	v_add_f32_e32 v104, 1.0, v105
	v_rcp_f32_e32 v104, v104
	v_mul_f32_e32 v97, v97, v100
	v_mul_f32_e32 v100, v102, v101
	v_mul_f32_e32 v98, v98, v100
	v_mul_f32_e32 v100, v103, v104
	v_cvt_pk_bf16_f32 v96, v96, v97
	v_mul_f32_e32 v99, v99, v100
	v_cvt_pk_bf16_f32 v97, v98, v99
	global_store_dwordx2 v[112:113], v[96:97], off offset:128
	v_mul_f32_e32 v96, 0xbfb8aa3b, v92
	v_exp_f32_e32 v98, v96
	v_mul_f32_e32 v99, 0xbfb8aa3b, v93
	v_exp_f32_e32 v99, v99
	v_or_b32_e32 v96, 32, v150
	v_add_f32_e32 v98, 1.0, v98
	v_rcp_f32_e32 v98, v98
	v_mad_i64_i32 v[96:97], s[48:49], v96, s68, v[140:141]
	v_lshl_add_u64 v[96:97], v[96:97], 0, v[142:143]
	v_mul_f32_e32 v92, v92, v98
	v_mul_f32_e32 v88, v88, v92
	v_add_f32_e32 v92, 1.0, v99
	v_mul_f32_e32 v98, 0xbfb8aa3b, v94
	v_rcp_f32_e32 v92, v92
	v_exp_f32_e32 v98, v98
	v_mul_f32_e32 v99, 0xbfb8aa3b, v95
	v_exp_f32_e32 v99, v99
	v_mul_f32_e32 v92, v93, v92
	v_add_f32_e32 v93, 1.0, v98
	v_rcp_f32_e32 v93, v93
	v_add_f32_e32 v98, 1.0, v99
	v_rcp_f32_e32 v98, v98
	v_mul_f32_e32 v89, v89, v92
	v_mul_f32_e32 v92, v94, v93
	v_mul_f32_e32 v93, 0xbfb8aa3b, v84
	v_exp_f32_e32 v93, v93
	v_mul_f32_e32 v90, v90, v92
	v_mul_f32_e32 v92, v95, v98
	v_mul_f32_e32 v91, v91, v92
	v_cvt_pk_bf16_f32 v88, v88, v89
	v_cvt_pk_bf16_f32 v89, v90, v91
	v_add_f32_e32 v90, 1.0, v93
	v_rcp_f32_e32 v90, v90
	v_mul_f32_e32 v91, 0xbfb8aa3b, v85
	v_exp_f32_e32 v91, v91
	global_store_dwordx2 v[96:97], v[88:89], off
	v_mul_f32_e32 v84, v84, v90
	v_mul_f32_e32 v80, v80, v84
	v_add_f32_e32 v84, 1.0, v91
	v_mul_f32_e32 v88, 0xbfb8aa3b, v86
	v_rcp_f32_e32 v84, v84
	v_exp_f32_e32 v88, v88
	v_mul_f32_e32 v89, 0xbfb8aa3b, v87
	v_exp_f32_e32 v89, v89
	v_mul_f32_e32 v84, v85, v84
	v_add_f32_e32 v85, 1.0, v88
	v_rcp_f32_e32 v85, v85
	v_add_f32_e32 v88, 1.0, v89
	v_rcp_f32_e32 v88, v88
	v_mul_f32_e32 v81, v81, v84
	v_mul_f32_e32 v84, v86, v85
	v_mul_f32_e32 v82, v82, v84
	v_mul_f32_e32 v84, v87, v88
	v_cvt_pk_bf16_f32 v80, v80, v81
	v_mul_f32_e32 v83, v83, v84
	v_cvt_pk_bf16_f32 v81, v82, v83
	global_store_dwordx2 v[96:97], v[80:81], off offset:128
	v_mul_f32_e32 v80, 0xbfb8aa3b, v76
	v_exp_f32_e32 v82, v80
	v_mul_f32_e32 v83, 0xbfb8aa3b, v77
	v_exp_f32_e32 v83, v83
	v_or_b32_e32 v80, 48, v150
	v_add_f32_e32 v82, 1.0, v82
	v_rcp_f32_e32 v82, v82
	v_mad_i64_i32 v[80:81], s[48:49], v80, s68, v[140:141]
	v_lshl_add_u64 v[80:81], v[80:81], 0, v[142:143]
	v_mul_f32_e32 v76, v76, v82
	v_mul_f32_e32 v72, v72, v76
	v_add_f32_e32 v76, 1.0, v83
	v_mul_f32_e32 v82, 0xbfb8aa3b, v78
	v_rcp_f32_e32 v76, v76
	v_exp_f32_e32 v82, v82
	v_mul_f32_e32 v83, 0xbfb8aa3b, v79
	v_exp_f32_e32 v83, v83
	v_mul_f32_e32 v76, v77, v76
	v_add_f32_e32 v77, 1.0, v82
	v_rcp_f32_e32 v77, v77
	v_add_f32_e32 v82, 1.0, v83
	v_rcp_f32_e32 v82, v82
	v_mul_f32_e32 v73, v73, v76
	v_mul_f32_e32 v76, v78, v77
	v_mul_f32_e32 v77, 0xbfb8aa3b, v68
	v_exp_f32_e32 v77, v77
	v_mul_f32_e32 v74, v74, v76
	v_mul_f32_e32 v76, v79, v82
	v_mul_f32_e32 v75, v75, v76
	v_cvt_pk_bf16_f32 v72, v72, v73
	v_cvt_pk_bf16_f32 v73, v74, v75
	v_add_f32_e32 v74, 1.0, v77
	v_rcp_f32_e32 v74, v74
	v_mul_f32_e32 v75, 0xbfb8aa3b, v69
	v_exp_f32_e32 v75, v75
	global_store_dwordx2 v[80:81], v[72:73], off
	v_mul_f32_e32 v68, v68, v74
	v_mul_f32_e32 v64, v64, v68
	v_add_f32_e32 v68, 1.0, v75
	v_mul_f32_e32 v72, 0xbfb8aa3b, v70
	v_rcp_f32_e32 v68, v68
	v_exp_f32_e32 v72, v72
	v_mul_f32_e32 v73, 0xbfb8aa3b, v71
	v_exp_f32_e32 v73, v73
	v_mul_f32_e32 v68, v69, v68
	v_add_f32_e32 v69, 1.0, v72
	v_rcp_f32_e32 v69, v69
	v_add_f32_e32 v72, 1.0, v73
	v_rcp_f32_e32 v72, v72
	v_mul_f32_e32 v65, v65, v68
	v_mul_f32_e32 v68, v70, v69
	v_mul_f32_e32 v66, v66, v68
	v_mul_f32_e32 v68, v71, v72
	v_cvt_pk_bf16_f32 v64, v64, v65
	v_mul_f32_e32 v67, v67, v68
	v_cvt_pk_bf16_f32 v65, v66, v67
	global_store_dwordx2 v[80:81], v[64:65], off offset:128
	v_mul_f32_e32 v64, 0xbfb8aa3b, v60
	v_exp_f32_e32 v66, v64
	v_mul_f32_e32 v67, 0xbfb8aa3b, v61
	v_exp_f32_e32 v67, v67
	v_add_u32_e32 v64, 0x80, v150
	v_add_f32_e32 v66, 1.0, v66
	v_rcp_f32_e32 v66, v66
	v_mad_i64_i32 v[64:65], s[48:49], v64, s68, v[140:141]
	v_lshl_add_u64 v[64:65], v[64:65], 0, v[142:143]
	v_mul_f32_e32 v60, v60, v66
	v_mul_f32_e32 v56, v56, v60
	v_add_f32_e32 v60, 1.0, v67
	v_mul_f32_e32 v66, 0xbfb8aa3b, v62
	v_rcp_f32_e32 v60, v60
	v_exp_f32_e32 v66, v66
	v_mul_f32_e32 v67, 0xbfb8aa3b, v63
	v_exp_f32_e32 v67, v67
	v_mul_f32_e32 v60, v61, v60
	v_add_f32_e32 v61, 1.0, v66
	v_rcp_f32_e32 v61, v61
	v_add_f32_e32 v66, 1.0, v67
	v_rcp_f32_e32 v66, v66
	v_mul_f32_e32 v57, v57, v60
	v_mul_f32_e32 v60, v62, v61
	v_mul_f32_e32 v61, 0xbfb8aa3b, v52
	v_exp_f32_e32 v61, v61
	v_mul_f32_e32 v58, v58, v60
	v_mul_f32_e32 v60, v63, v66
	v_mul_f32_e32 v59, v59, v60
	v_cvt_pk_bf16_f32 v56, v56, v57
	v_cvt_pk_bf16_f32 v57, v58, v59
	v_add_f32_e32 v58, 1.0, v61
	v_rcp_f32_e32 v58, v58
	v_mul_f32_e32 v59, 0xbfb8aa3b, v53
	v_exp_f32_e32 v59, v59
	global_store_dwordx2 v[64:65], v[56:57], off
	v_mul_f32_e32 v52, v52, v58
	v_mul_f32_e32 v48, v48, v52
	v_add_f32_e32 v52, 1.0, v59
	v_mul_f32_e32 v56, 0xbfb8aa3b, v54
	v_rcp_f32_e32 v52, v52
	v_exp_f32_e32 v56, v56
	v_mul_f32_e32 v57, 0xbfb8aa3b, v55
	v_exp_f32_e32 v57, v57
	v_mul_f32_e32 v52, v53, v52
	v_add_f32_e32 v53, 1.0, v56
	v_rcp_f32_e32 v53, v53
	v_add_f32_e32 v56, 1.0, v57
	v_rcp_f32_e32 v56, v56
	v_mul_f32_e32 v49, v49, v52
	v_mul_f32_e32 v52, v54, v53
	v_mul_f32_e32 v50, v50, v52
	v_mul_f32_e32 v52, v55, v56
	v_cvt_pk_bf16_f32 v48, v48, v49
	v_mul_f32_e32 v51, v51, v52
	v_cvt_pk_bf16_f32 v49, v50, v51
	global_store_dwordx2 v[64:65], v[48:49], off offset:128
	v_mul_f32_e32 v48, 0xbfb8aa3b, v44
	v_exp_f32_e32 v50, v48
	v_mul_f32_e32 v51, 0xbfb8aa3b, v45
	v_exp_f32_e32 v51, v51
	v_add_u32_e32 v48, 0x90, v150
	v_add_f32_e32 v50, 1.0, v50
	v_rcp_f32_e32 v50, v50
	v_mad_i64_i32 v[48:49], s[48:49], v48, s68, v[140:141]
	v_lshl_add_u64 v[48:49], v[48:49], 0, v[142:143]
	v_mul_f32_e32 v44, v44, v50
	v_mul_f32_e32 v40, v40, v44
	v_add_f32_e32 v44, 1.0, v51
	v_mul_f32_e32 v50, 0xbfb8aa3b, v46
	v_rcp_f32_e32 v44, v44
	v_exp_f32_e32 v50, v50
	v_mul_f32_e32 v51, 0xbfb8aa3b, v47
	v_exp_f32_e32 v51, v51
	v_mul_f32_e32 v44, v45, v44
	v_add_f32_e32 v45, 1.0, v50
	v_rcp_f32_e32 v45, v45
	v_add_f32_e32 v50, 1.0, v51
	v_rcp_f32_e32 v50, v50
	v_mul_f32_e32 v41, v41, v44
	v_mul_f32_e32 v44, v46, v45
	v_mul_f32_e32 v45, 0xbfb8aa3b, v36
	v_exp_f32_e32 v45, v45
	v_mul_f32_e32 v42, v42, v44
	v_mul_f32_e32 v44, v47, v50
	v_mul_f32_e32 v43, v43, v44
	v_cvt_pk_bf16_f32 v40, v40, v41
	v_cvt_pk_bf16_f32 v41, v42, v43
	v_add_f32_e32 v42, 1.0, v45
	v_rcp_f32_e32 v42, v42
	v_mul_f32_e32 v43, 0xbfb8aa3b, v37
	v_exp_f32_e32 v43, v43
	global_store_dwordx2 v[48:49], v[40:41], off
	v_mul_f32_e32 v36, v36, v42
	v_mul_f32_e32 v32, v32, v36
	v_add_f32_e32 v36, 1.0, v43
	v_mul_f32_e32 v40, 0xbfb8aa3b, v38
	v_rcp_f32_e32 v36, v36
	v_exp_f32_e32 v40, v40
	v_mul_f32_e32 v41, 0xbfb8aa3b, v39
	v_exp_f32_e32 v41, v41
	v_mul_f32_e32 v36, v37, v36
	v_add_f32_e32 v37, 1.0, v40
	v_rcp_f32_e32 v37, v37
	v_add_f32_e32 v40, 1.0, v41
	v_rcp_f32_e32 v40, v40
	v_mul_f32_e32 v33, v33, v36
	v_mul_f32_e32 v36, v38, v37
	v_mul_f32_e32 v34, v34, v36
	v_mul_f32_e32 v36, v39, v40
	v_cvt_pk_bf16_f32 v32, v32, v33
	v_mul_f32_e32 v35, v35, v36
	v_cvt_pk_bf16_f32 v33, v34, v35
	global_store_dwordx2 v[48:49], v[32:33], off offset:128
	v_mul_f32_e32 v32, 0xbfb8aa3b, v28
	v_exp_f32_e32 v34, v32
	v_mul_f32_e32 v35, 0xbfb8aa3b, v29
	v_exp_f32_e32 v35, v35
	v_add_u32_e32 v32, 0xa0, v150
	v_add_f32_e32 v34, 1.0, v34
	v_rcp_f32_e32 v34, v34
	v_mad_i64_i32 v[32:33], s[48:49], v32, s68, v[140:141]
	v_lshl_add_u64 v[32:33], v[32:33], 0, v[142:143]
	v_mul_f32_e32 v28, v28, v34
	v_mul_f32_e32 v24, v24, v28
	v_add_f32_e32 v28, 1.0, v35
	v_mul_f32_e32 v34, 0xbfb8aa3b, v30
	v_rcp_f32_e32 v28, v28
	v_exp_f32_e32 v34, v34
	v_mul_f32_e32 v35, 0xbfb8aa3b, v31
	v_exp_f32_e32 v35, v35
	v_mul_f32_e32 v28, v29, v28
	v_add_f32_e32 v29, 1.0, v34
	v_rcp_f32_e32 v29, v29
	v_add_f32_e32 v34, 1.0, v35
	v_rcp_f32_e32 v34, v34
	v_mul_f32_e32 v25, v25, v28
	v_mul_f32_e32 v28, v30, v29
	v_mul_f32_e32 v29, 0xbfb8aa3b, v20
	v_exp_f32_e32 v29, v29
	v_mul_f32_e32 v26, v26, v28
	v_mul_f32_e32 v28, v31, v34
	v_mul_f32_e32 v27, v27, v28
	v_cvt_pk_bf16_f32 v24, v24, v25
	v_cvt_pk_bf16_f32 v25, v26, v27
	v_add_f32_e32 v26, 1.0, v29
	v_rcp_f32_e32 v26, v26
	v_mul_f32_e32 v27, 0xbfb8aa3b, v21
	v_exp_f32_e32 v27, v27
	global_store_dwordx2 v[32:33], v[24:25], off
	v_mul_f32_e32 v20, v20, v26
	v_mul_f32_e32 v16, v16, v20
	v_add_f32_e32 v20, 1.0, v27
	v_mul_f32_e32 v24, 0xbfb8aa3b, v22
	v_rcp_f32_e32 v20, v20
	v_exp_f32_e32 v24, v24
	v_mul_f32_e32 v25, 0xbfb8aa3b, v23
	v_exp_f32_e32 v25, v25
	v_mul_f32_e32 v20, v21, v20
	v_add_f32_e32 v21, 1.0, v24
	v_rcp_f32_e32 v21, v21
	v_add_f32_e32 v24, 1.0, v25
	v_rcp_f32_e32 v24, v24
	v_mul_f32_e32 v17, v17, v20
	v_mul_f32_e32 v20, v22, v21
	v_mul_f32_e32 v18, v18, v20
	v_mul_f32_e32 v20, v23, v24
	v_cvt_pk_bf16_f32 v16, v16, v17
	v_mul_f32_e32 v19, v19, v20
	v_cvt_pk_bf16_f32 v17, v18, v19
	global_store_dwordx2 v[32:33], v[16:17], off offset:128
	v_mul_f32_e32 v16, 0xbfb8aa3b, v12
	v_exp_f32_e32 v18, v16
	v_mul_f32_e32 v19, 0xbfb8aa3b, v13
	v_exp_f32_e32 v19, v19
	v_add_u32_e32 v16, 0xb0, v150
	v_add_f32_e32 v18, 1.0, v18
	v_rcp_f32_e32 v18, v18
	v_mad_i64_i32 v[16:17], s[48:49], v16, s68, v[140:141]
	v_lshl_add_u64 v[16:17], v[16:17], 0, v[142:143]
	v_mul_f32_e32 v12, v12, v18
	v_mul_f32_e32 v8, v8, v12
	v_add_f32_e32 v12, 1.0, v19
	v_mul_f32_e32 v18, 0xbfb8aa3b, v14
	v_rcp_f32_e32 v12, v12
	v_exp_f32_e32 v18, v18
	v_mul_f32_e32 v19, 0xbfb8aa3b, v15
	v_exp_f32_e32 v19, v19
	v_mul_f32_e32 v12, v13, v12
	v_add_f32_e32 v13, 1.0, v18
	v_rcp_f32_e32 v13, v13
	v_add_f32_e32 v18, 1.0, v19
	v_rcp_f32_e32 v18, v18
	v_mul_f32_e32 v9, v9, v12
	v_mul_f32_e32 v12, v14, v13
	v_mul_f32_e32 v13, 0xbfb8aa3b, v4
	v_exp_f32_e32 v13, v13
	v_mul_f32_e32 v10, v10, v12
	v_mul_f32_e32 v12, v15, v18
	v_mul_f32_e32 v11, v11, v12
	v_cvt_pk_bf16_f32 v8, v8, v9
	v_cvt_pk_bf16_f32 v9, v10, v11
	v_add_f32_e32 v10, 1.0, v13
	v_rcp_f32_e32 v10, v10
	v_mul_f32_e32 v11, 0xbfb8aa3b, v5
	v_exp_f32_e32 v11, v11
	global_store_dwordx2 v[16:17], v[8:9], off
	v_mul_f32_e32 v4, v4, v10
	v_mul_f32_e32 v0, v0, v4
	v_add_f32_e32 v4, 1.0, v11
	v_mul_f32_e32 v8, 0xbfb8aa3b, v6
	v_rcp_f32_e32 v4, v4
	v_exp_f32_e32 v8, v8
	v_mul_f32_e32 v9, 0xbfb8aa3b, v7
	v_exp_f32_e32 v9, v9
	v_mul_f32_e32 v4, v5, v4
	v_add_f32_e32 v5, 1.0, v8
	v_rcp_f32_e32 v5, v5
	v_add_f32_e32 v8, 1.0, v9
	v_rcp_f32_e32 v8, v8
	v_mul_f32_e32 v1, v1, v4
	v_mul_f32_e32 v4, v6, v5
	v_mul_f32_e32 v2, v2, v4
	v_mul_f32_e32 v4, v7, v8
	s_andn2_b64 vcc, exec, s[10:11]
	s_mov_b64 s[10:11], -1
	v_mul_f32_e32 v3, v3, v4
	v_cvt_pk_bf16_f32 v0, v0, v1
	v_cvt_pk_bf16_f32 v1, v2, v3
	global_store_dwordx2 v[16:17], v[0:1], off offset:128
	s_cbranch_vccnz .LBB0_720
	s_andn2_b64 vcc, exec, s[0:1]
	s_cbranch_vccnz .LBB0_719
	s_barrier
	s_branch .LBB0_719

.LBB0_807:
	v_lshl_add_u32 v152, s82, 8, v146
	v_lshl_or_b32 v144, s83, 8, v148
	v_ashrrev_i32_e32 v145, 31, v144
	v_ashrrev_i32_e32 v153, 31, v152
	v_lshl_add_u64 v[154:155], v[144:145], 1, s[24:25]
	v_lshlrev_b64 v[144:145], 11, v[152:153]
	v_lshl_add_u64 v[144:145], v[154:155], 0, v[144:145]
	s_nop 15
	s_nop 7
	v_cvt_pk_bf16_f32 v124, v124, v125
	v_cvt_pk_bf16_f32 v125, v126, v127
	v_cvt_pk_bf16_f32 v126, v120, v121
	v_cvt_pk_bf16_f32 v127, v122, v123
	global_store_dwordx4 v[144:145], v[124:127], off
	v_cvt_pk_bf16_f32 v112, v112, v113
	v_cvt_pk_bf16_f32 v113, v114, v115
	v_cvt_pk_bf16_f32 v114, v104, v105
	v_or_b32_e32 v104, 16, v152
	v_ashrrev_i32_e32 v105, 31, v104
	v_lshlrev_b64 v[104:105], 11, v[104:105]
	v_cvt_pk_bf16_f32 v115, v106, v107
	global_store_dwordx4 v[144:145], v[112:115], off offset:256
	s_nop 1
	v_lshl_add_u64 v[112:113], v[154:155], 0, v[104:105]
	v_cvt_pk_bf16_f32 v104, v116, v117
	v_cvt_pk_bf16_f32 v105, v118, v119
	v_cvt_pk_bf16_f32 v106, v108, v109
	v_cvt_pk_bf16_f32 v107, v110, v111
	global_store_dwordx4 v[112:113], v[104:107], off
	v_cvt_pk_bf16_f32 v96, v96, v97
	v_cvt_pk_bf16_f32 v97, v98, v99
	v_cvt_pk_bf16_f32 v98, v88, v89
	v_or_b32_e32 v88, 32, v152
	v_ashrrev_i32_e32 v89, 31, v88
	v_lshlrev_b64 v[88:89], 11, v[88:89]
	v_cvt_pk_bf16_f32 v99, v90, v91
	global_store_dwordx4 v[112:113], v[96:99], off offset:256
	s_nop 1
	v_lshl_add_u64 v[96:97], v[154:155], 0, v[88:89]
	v_cvt_pk_bf16_f32 v88, v100, v101
	v_cvt_pk_bf16_f32 v89, v102, v103
	v_cvt_pk_bf16_f32 v90, v92, v93
	v_cvt_pk_bf16_f32 v91, v94, v95
	global_store_dwordx4 v[96:97], v[88:91], off
	v_cvt_pk_bf16_f32 v80, v80, v81
	v_cvt_pk_bf16_f32 v81, v82, v83
	v_cvt_pk_bf16_f32 v82, v72, v73
	v_or_b32_e32 v72, 48, v152
	s_and_b64 vcc, exec, s[18:19]
	s_cbranch_vccz .Lxb_5
	s_barrier
.Lxb_5:
	v_ashrrev_i32_e32 v73, 31, v72
	v_lshlrev_b64 v[72:73], 11, v[72:73]
	v_cvt_pk_bf16_f32 v83, v74, v75
	global_store_dwordx4 v[96:97], v[80:83], off offset:256
	s_nop 1
	v_lshl_add_u64 v[80:81], v[154:155], 0, v[72:73]
	v_cvt_pk_bf16_f32 v72, v84, v85
	v_cvt_pk_bf16_f32 v73, v86, v87
	v_cvt_pk_bf16_f32 v74, v76, v77
	v_cvt_pk_bf16_f32 v75, v78, v79
	global_store_dwordx4 v[80:81], v[72:75], off
	v_cvt_pk_bf16_f32 v68, v68, v69
	v_cvt_pk_bf16_f32 v69, v70, v71
	v_cvt_pk_bf16_f32 v70, v64, v65
	v_cvt_pk_bf16_f32 v71, v66, v67
	global_store_dwordx4 v[80:81], v[68:71], off offset:256
	v_cvt_pk_bf16_f32 v60, v60, v61
	v_cvt_pk_bf16_f32 v61, v62, v63
	v_cvt_pk_bf16_f32 v62, v56, v57
	v_add_co_u32_e32 v56, vcc, s72, v144
	v_lshl_add_u64 v[64:65], v[144:145], 0, s[30:31]
	s_nop 0
	v_addc_co_u32_e32 v57, vcc, 0, v145, vcc
	v_cvt_pk_bf16_f32 v63, v58, v59
	global_store_dwordx4 v[56:57], v[60:63], off
	v_cvt_pk_bf16_f32 v48, v48, v49
	v_cvt_pk_bf16_f32 v49, v50, v51
	v_cvt_pk_bf16_f32 v50, v40, v41
	v_cvt_pk_bf16_f32 v51, v42, v43
	global_store_dwordx4 v[64:65], v[48:51], off offset:256
	v_cvt_pk_bf16_f32 v40, v52, v53
	v_cvt_pk_bf16_f32 v41, v54, v55
	v_cvt_pk_bf16_f32 v42, v44, v45
	v_add_co_u32_e32 v44, vcc, s73, v144
	s_nop 0
	v_lshl_add_u64 v[48:49], v[144:145], 0, s[36:37]
	v_addc_co_u32_e32 v45, vcc, 0, v145, vcc
	v_cvt_pk_bf16_f32 v43, v46, v47
	global_store_dwordx4 v[44:45], v[40:43], off
	v_cvt_pk_bf16_f32 v32, v32, v33
	v_cvt_pk_bf16_f32 v33, v34, v35
	v_cvt_pk_bf16_f32 v34, v24, v25
	v_cvt_pk_bf16_f32 v35, v26, v27
	global_store_dwordx4 v[48:49], v[32:35], off offset:256
	v_cvt_pk_bf16_f32 v24, v36, v37
	v_cvt_pk_bf16_f32 v25, v38, v39
	v_cvt_pk_bf16_f32 v26, v28, v29
	v_add_co_u32_e32 v28, vcc, s74, v144
	s_nop 0
	v_lshl_add_u64 v[32:33], v[144:145], 0, s[44:45]
	v_addc_co_u32_e32 v29, vcc, 0, v145, vcc
	v_cvt_pk_bf16_f32 v27, v30, v31
	global_store_dwordx4 v[28:29], v[24:27], off
	v_cvt_pk_bf16_f32 v16, v16, v17
	v_cvt_pk_bf16_f32 v17, v18, v19
	v_cvt_pk_bf16_f32 v18, v8, v9
	v_cvt_pk_bf16_f32 v19, v10, v11
	global_store_dwordx4 v[32:33], v[16:19], off offset:256
	v_cvt_pk_bf16_f32 v8, v20, v21
	v_cvt_pk_bf16_f32 v9, v22, v23
	v_cvt_pk_bf16_f32 v10, v12, v13
	v_add_co_u32_e32 v12, vcc, s75, v144
	s_nop 0
	v_lshl_add_u64 v[16:17], v[144:145], 0, s[46:47]
	v_addc_co_u32_e32 v13, vcc, 0, v145, vcc
	s_and_b64 vcc, exec, s[10:11]
	s_mov_b64 s[10:11], -1
	v_cvt_pk_bf16_f32 v11, v14, v15
	global_store_dwordx4 v[12:13], v[8:11], off
	v_cvt_pk_bf16_f32 v4, v4, v5
	v_cvt_pk_bf16_f32 v5, v6, v7
	v_cvt_pk_bf16_f32 v6, v0, v1
	v_cvt_pk_bf16_f32 v7, v2, v3
	global_store_dwordx4 v[16:17], v[4:7], off offset:256
	s_cbranch_vccnz .LBB0_792
	s_andn2_b64 vcc, exec, s[0:1]
	s_cbranch_vccnz .LBB0_791
	s_barrier
	s_branch .LBB0_791

.LBB0_938:
	s_lshl_b32 s49, s59, 8
	s_or_b32 s49, s49, s74
	v_lshl_add_u32 v152, s58, 8, v146
	s_ashr_i32 s58, s49, 6
	s_ashr_i32 s59, s58, 31
	s_lshl_b64 s[60:61], s[58:59], 22
	v_ashrrev_i32_e32 v153, 31, v152
	v_lshl_add_u64 v[154:155], v[136:137], 0, s[60:61]
	v_cvt_pk_bf16_f32 v124, v124, v125
	v_cvt_pk_bf16_f32 v125, v126, v127
	v_cvt_pk_bf16_f32 v126, v120, v121
	v_lshlrev_b64 v[120:121], 7, v[152:153]
	v_cvt_pk_bf16_f32 v127, v122, v123
	v_lshl_add_u64 v[122:123], v[154:155], 0, v[120:121]
	global_store_dwordx4 v[122:123], v[124:127], off
	v_cvt_pk_bf16_f32 v116, v116, v117
	v_cvt_pk_bf16_f32 v117, v118, v119
	v_cvt_pk_bf16_f32 v118, v112, v113
	v_or_b32_e32 v112, 16, v152
	v_ashrrev_i32_e32 v113, 31, v112
	v_lshlrev_b64 v[112:113], 7, v[112:113]
	v_cvt_pk_bf16_f32 v119, v114, v115
	v_lshl_add_u64 v[114:115], v[154:155], 0, v[112:113]
	global_store_dwordx4 v[114:115], v[116:119], off
	v_cvt_pk_bf16_f32 v108, v108, v109
	v_cvt_pk_bf16_f32 v109, v110, v111
	v_cvt_pk_bf16_f32 v110, v104, v105
	v_or_b32_e32 v104, 32, v152
	v_ashrrev_i32_e32 v105, 31, v104
	v_lshlrev_b64 v[104:105], 7, v[104:105]
	v_cvt_pk_bf16_f32 v111, v106, v107
	v_lshl_add_u64 v[106:107], v[154:155], 0, v[104:105]
	global_store_dwordx4 v[106:107], v[108:111], off
	v_cvt_pk_bf16_f32 v100, v100, v101
	v_cvt_pk_bf16_f32 v101, v102, v103
	v_cvt_pk_bf16_f32 v102, v96, v97
	v_or_b32_e32 v96, 48, v152
	v_ashrrev_i32_e32 v97, 31, v96
	v_lshlrev_b64 v[96:97], 7, v[96:97]
	v_cvt_pk_bf16_f32 v103, v98, v99
	v_lshl_add_u64 v[98:99], v[154:155], 0, v[96:97]
	global_store_dwordx4 v[98:99], v[100:103], off
	v_cvt_pk_bf16_f32 v92, v92, v93
	v_cvt_pk_bf16_f32 v93, v94, v95
	v_cvt_pk_bf16_f32 v94, v88, v89
	v_lshl_add_u64 v[88:89], v[120:121], 0, s[18:19]
	v_cvt_pk_bf16_f32 v95, v90, v91
	v_lshl_add_u64 v[90:91], v[154:155], 0, v[88:89]
	s_and_b64 vcc, exec, s[16:17]
	s_cbranch_vccz .Lxb_6
	s_barrier
.Lxb_6:
	global_store_dwordx4 v[90:91], v[92:95], off
	v_cvt_pk_bf16_f32 v84, v84, v85
	v_cvt_pk_bf16_f32 v85, v86, v87
	v_cvt_pk_bf16_f32 v86, v80, v81
	v_lshl_add_u64 v[80:81], v[120:121], 0, s[36:37]
	v_cvt_pk_bf16_f32 v87, v82, v83
	v_lshl_add_u64 v[82:83], v[154:155], 0, v[80:81]
	global_store_dwordx4 v[82:83], v[84:87], off
	v_cvt_pk_bf16_f32 v72, v72, v73
	v_cvt_pk_bf16_f32 v73, v74, v75
	v_cvt_pk_bf16_f32 v74, v64, v65
	v_lshl_add_u64 v[64:65], v[120:121], 0, s[44:45]
	v_cvt_pk_bf16_f32 v75, v66, v67
	v_lshl_add_u64 v[66:67], v[154:155], 0, v[64:65]
	s_or_b32 s58, s58, 2
	global_store_dwordx4 v[66:67], v[72:75], off
	v_lshl_add_u64 v[66:67], v[120:121], 0, s[46:47]
	s_ashr_i32 s59, s58, 31
	v_cvt_pk_bf16_f32 v56, v56, v57
	v_cvt_pk_bf16_f32 v57, v58, v59
	v_cvt_pk_bf16_f32 v58, v48, v49
	v_lshl_add_u64 v[48:49], v[154:155], 0, v[66:67]
	s_lshl_b64 s[58:59], s[58:59], 22
	v_cvt_pk_bf16_f32 v59, v50, v51
	global_store_dwordx4 v[48:49], v[56:59], off
	v_cvt_pk_bf16_f32 v48, v76, v77
	v_cvt_pk_bf16_f32 v49, v78, v79
	v_cvt_pk_bf16_f32 v50, v68, v69
	v_cvt_pk_bf16_f32 v51, v70, v71
	s_andn2_b64 vcc, exec, s[10:11]
	s_nop 0
	v_lshl_add_u64 v[56:57], v[136:137], 0, s[58:59]
	v_lshl_add_u64 v[58:59], v[56:57], 0, v[120:121]
	global_store_dwordx4 v[58:59], v[48:51], off
	s_mov_b64 s[10:11], -1
	s_nop 0
	v_cvt_pk_bf16_f32 v48, v60, v61
	v_cvt_pk_bf16_f32 v49, v62, v63
	v_cvt_pk_bf16_f32 v50, v52, v53
	v_lshl_add_u64 v[52:53], v[56:57], 0, v[112:113]
	v_cvt_pk_bf16_f32 v51, v54, v55
	global_store_dwordx4 v[52:53], v[48:51], off
	v_cvt_pk_bf16_f32 v44, v44, v45
	v_cvt_pk_bf16_f32 v45, v46, v47
	v_cvt_pk_bf16_f32 v46, v40, v41
	v_lshl_add_u64 v[40:41], v[56:57], 0, v[104:105]
	v_cvt_pk_bf16_f32 v47, v42, v43
	global_store_dwordx4 v[40:41], v[44:47], off
	v_cvt_pk_bf16_f32 v36, v36, v37
	v_cvt_pk_bf16_f32 v37, v38, v39
	v_cvt_pk_bf16_f32 v38, v32, v33
	v_lshl_add_u64 v[32:33], v[56:57], 0, v[96:97]
	v_cvt_pk_bf16_f32 v39, v34, v35
	global_store_dwordx4 v[32:33], v[36:39], off
	v_cvt_pk_bf16_f32 v28, v28, v29
	v_cvt_pk_bf16_f32 v29, v30, v31
	v_cvt_pk_bf16_f32 v30, v24, v25
	v_lshl_add_u64 v[24:25], v[56:57], 0, v[88:89]
	v_cvt_pk_bf16_f32 v31, v26, v27
	global_store_dwordx4 v[24:25], v[28:31], off
	v_cvt_pk_bf16_f32 v20, v20, v21
	v_cvt_pk_bf16_f32 v21, v22, v23
	v_cvt_pk_bf16_f32 v22, v16, v17
	v_lshl_add_u64 v[16:17], v[56:57], 0, v[80:81]
	v_cvt_pk_bf16_f32 v23, v18, v19
	global_store_dwordx4 v[16:17], v[20:23], off
	v_cvt_pk_bf16_f32 v12, v12, v13
	v_cvt_pk_bf16_f32 v13, v14, v15
	v_cvt_pk_bf16_f32 v14, v8, v9
	v_lshl_add_u64 v[8:9], v[56:57], 0, v[64:65]
	v_cvt_pk_bf16_f32 v15, v10, v11
	global_store_dwordx4 v[8:9], v[12:15], off
	v_cvt_pk_bf16_f32 v4, v4, v5
	v_cvt_pk_bf16_f32 v5, v6, v7
	v_cvt_pk_bf16_f32 v6, v0, v1
	v_lshl_add_u64 v[0:1], v[56:57], 0, v[66:67]
	v_cvt_pk_bf16_f32 v7, v2, v3
	global_store_dwordx4 v[0:1], v[4:7], off
	s_cbranch_vccnz .LBB0_927
	s_andn2_b64 vcc, exec, s[0:1]
	s_cbranch_vccnz .LBB0_926
	s_barrier
	s_branch .LBB0_926

.LBB0_954:
	v_mul_f32_e32 v151, 0xbfb8aa3b, v124
	v_exp_f32_e32 v151, v151
	v_mul_f32_e32 v154, 0xbfb8aa3b, v125
	v_exp_f32_e32 v154, v154
	v_lshl_or_b32 v142, s71, 7, v146
	v_add_f32_e32 v151, 1.0, v151
	v_rcp_f32_e32 v151, v151
	v_lshl_add_u32 v150, s48, 8, v144
	v_ashrrev_i32_e32 v143, 31, v142
	v_mov_b64_e32 v[140:141], s[22:23]
	v_mul_f32_e32 v124, v124, v151
	v_mul_f32_e32 v120, v120, v124
	v_add_f32_e32 v124, 1.0, v154
	v_mul_f32_e32 v151, 0xbfb8aa3b, v126
	v_rcp_f32_e32 v124, v124
	v_exp_f32_e32 v151, v151
	v_mul_f32_e32 v154, 0xbfb8aa3b, v127
	v_exp_f32_e32 v154, v154
	v_mul_f32_e32 v124, v125, v124
	v_add_f32_e32 v125, 1.0, v151
	v_rcp_f32_e32 v125, v125
	v_add_f32_e32 v151, 1.0, v154
	v_rcp_f32_e32 v151, v151
	v_mul_f32_e32 v121, v121, v124
	v_mul_f32_e32 v124, v126, v125
	v_mul_f32_e32 v125, 0xbfb8aa3b, v116
	v_exp_f32_e32 v125, v125
	v_mul_f32_e32 v122, v122, v124
	v_mul_f32_e32 v124, v127, v151
	v_mul_f32_e32 v123, v123, v124
	v_cvt_pk_bf16_f32 v120, v120, v121
	v_cvt_pk_bf16_f32 v121, v122, v123
	v_add_f32_e32 v122, 1.0, v125
	v_rcp_f32_e32 v122, v122
	v_mul_f32_e32 v123, 0xbfb8aa3b, v117
	v_exp_f32_e32 v123, v123
	v_mad_i64_i32 v[152:153], s[52:53], v150, s70, v[140:141]
	v_lshlrev_b64 v[142:143], 1, v[142:143]
	v_lshl_add_u64 v[152:153], v[152:153], 0, v[142:143]
	v_mul_f32_e32 v116, v116, v122
	global_store_dwordx2 v[152:153], v[120:121], off
	v_mul_f32_e32 v112, v112, v116
	v_add_f32_e32 v116, 1.0, v123
	v_mul_f32_e32 v120, 0xbfb8aa3b, v118
	v_rcp_f32_e32 v116, v116
	v_exp_f32_e32 v120, v120
	v_mul_f32_e32 v121, 0xbfb8aa3b, v119
	v_exp_f32_e32 v121, v121
	v_mul_f32_e32 v116, v117, v116
	v_add_f32_e32 v117, 1.0, v120
	v_rcp_f32_e32 v117, v117
	v_add_f32_e32 v120, 1.0, v121
	v_rcp_f32_e32 v120, v120
	v_mul_f32_e32 v113, v113, v116
	v_mul_f32_e32 v116, v118, v117
	v_mul_f32_e32 v114, v114, v116
	v_mul_f32_e32 v116, v119, v120
	v_cvt_pk_bf16_f32 v112, v112, v113
	v_mul_f32_e32 v115, v115, v116
	v_cvt_pk_bf16_f32 v113, v114, v115
	global_store_dwordx2 v[152:153], v[112:113], off offset:128
	v_mul_f32_e32 v112, 0xbfb8aa3b, v108
	v_exp_f32_e32 v114, v112
	v_mul_f32_e32 v115, 0xbfb8aa3b, v109
	s_and_b64 vcc, exec, s[16:17]
	s_cbranch_vccz .Lxb_7
	s_barrier
.Lxb_7:
	v_exp_f32_e32 v115, v115
	v_or_b32_e32 v112, 16, v150
	v_add_f32_e32 v114, 1.0, v114
	v_rcp_f32_e32 v114, v114
	v_mad_i64_i32 v[112:113], s[52:53], v112, s70, v[140:141]
	v_lshl_add_u64 v[112:113], v[112:113], 0, v[142:143]
	v_mul_f32_e32 v108, v108, v114
	v_mul_f32_e32 v104, v104, v108
	v_add_f32_e32 v108, 1.0, v115
	v_mul_f32_e32 v114, 0xbfb8aa3b, v110
	v_rcp_f32_e32 v108, v108
	v_exp_f32_e32 v114, v114
	v_mul_f32_e32 v115, 0xbfb8aa3b, v111
	v_exp_f32_e32 v115, v115
	v_mul_f32_e32 v108, v109, v108
	v_add_f32_e32 v109, 1.0, v114
	v_rcp_f32_e32 v109, v109
	v_add_f32_e32 v114, 1.0, v115
	v_rcp_f32_e32 v114, v114
	v_mul_f32_e32 v105, v105, v108
	v_mul_f32_e32 v108, v110, v109
	v_mul_f32_e32 v109, 0xbfb8aa3b, v100
	v_exp_f32_e32 v109, v109
	v_mul_f32_e32 v106, v106, v108
	v_mul_f32_e32 v108, v111, v114
	v_mul_f32_e32 v107, v107, v108
	v_cvt_pk_bf16_f32 v104, v104, v105
	v_cvt_pk_bf16_f32 v105, v106, v107
	v_add_f32_e32 v106, 1.0, v109
	v_rcp_f32_e32 v106, v106
	v_mul_f32_e32 v107, 0xbfb8aa3b, v101
	v_exp_f32_e32 v107, v107
	global_store_dwordx2 v[112:113], v[104:105], off
	v_mul_f32_e32 v100, v100, v106
	v_mul_f32_e32 v96, v96, v100
	v_add_f32_e32 v100, 1.0, v107
	v_mul_f32_e32 v104, 0xbfb8aa3b, v102
	v_rcp_f32_e32 v100, v100
	v_exp_f32_e32 v104, v104
	v_mul_f32_e32 v105, 0xbfb8aa3b, v103
	v_exp_f32_e32 v105, v105
	v_mul_f32_e32 v100, v101, v100
	v_add_f32_e32 v101, 1.0, v104
	v_rcp_f32_e32 v101, v101
	v_add_f32_e32 v104, 1.0, v105
	v_rcp_f32_e32 v104, v104
	v_mul_f32_e32 v97, v97, v100
	v_mul_f32_e32 v100, v102, v101
	v_mul_f32_e32 v98, v98, v100
	v_mul_f32_e32 v100, v103, v104
	v_cvt_pk_bf16_f32 v96, v96, v97
	v_mul_f32_e32 v99, v99, v100
	v_cvt_pk_bf16_f32 v97, v98, v99
	global_store_dwordx2 v[112:113], v[96:97], off offset:128
	v_mul_f32_e32 v96, 0xbfb8aa3b, v92
	v_exp_f32_e32 v98, v96
	v_mul_f32_e32 v99, 0xbfb8aa3b, v93
	v_exp_f32_e32 v99, v99
	v_or_b32_e32 v96, 32, v150
	v_add_f32_e32 v98, 1.0, v98
	v_rcp_f32_e32 v98, v98
	v_mad_i64_i32 v[96:97], s[52:53], v96, s70, v[140:141]
	v_lshl_add_u64 v[96:97], v[96:97], 0, v[142:143]
	v_mul_f32_e32 v92, v92, v98
	v_mul_f32_e32 v88, v88, v92
	v_add_f32_e32 v92, 1.0, v99
	v_mul_f32_e32 v98, 0xbfb8aa3b, v94
	v_rcp_f32_e32 v92, v92
	v_exp_f32_e32 v98, v98
	v_mul_f32_e32 v99, 0xbfb8aa3b, v95
	v_exp_f32_e32 v99, v99
	v_mul_f32_e32 v92, v93, v92
	v_add_f32_e32 v93, 1.0, v98
	v_rcp_f32_e32 v93, v93
	v_add_f32_e32 v98, 1.0, v99
	v_rcp_f32_e32 v98, v98
	v_mul_f32_e32 v89, v89, v92
	v_mul_f32_e32 v92, v94, v93
	v_mul_f32_e32 v93, 0xbfb8aa3b, v84
	v_exp_f32_e32 v93, v93
	v_mul_f32_e32 v90, v90, v92
	v_mul_f32_e32 v92, v95, v98
	v_mul_f32_e32 v91, v91, v92
	v_cvt_pk_bf16_f32 v88, v88, v89
	v_cvt_pk_bf16_f32 v89, v90, v91
	v_add_f32_e32 v90, 1.0, v93
	v_rcp_f32_e32 v90, v90
	v_mul_f32_e32 v91, 0xbfb8aa3b, v85
	v_exp_f32_e32 v91, v91
	global_store_dwordx2 v[96:97], v[88:89], off
	v_mul_f32_e32 v84, v84, v90
	v_mul_f32_e32 v80, v80, v84
	v_add_f32_e32 v84, 1.0, v91
	v_mul_f32_e32 v88, 0xbfb8aa3b, v86
	v_rcp_f32_e32 v84, v84
	v_exp_f32_e32 v88, v88
	v_mul_f32_e32 v89, 0xbfb8aa3b, v87
	v_exp_f32_e32 v89, v89
	v_mul_f32_e32 v84, v85, v84
	v_add_f32_e32 v85, 1.0, v88
	v_rcp_f32_e32 v85, v85
	v_add_f32_e32 v88, 1.0, v89
	v_rcp_f32_e32 v88, v88
	v_mul_f32_e32 v81, v81, v84
	v_mul_f32_e32 v84, v86, v85
	v_mul_f32_e32 v82, v82, v84
	v_mul_f32_e32 v84, v87, v88
	v_cvt_pk_bf16_f32 v80, v80, v81
	v_mul_f32_e32 v83, v83, v84
	v_cvt_pk_bf16_f32 v81, v82, v83
	global_store_dwordx2 v[96:97], v[80:81], off offset:128
	v_mul_f32_e32 v80, 0xbfb8aa3b, v76
	v_exp_f32_e32 v82, v80
	v_mul_f32_e32 v83, 0xbfb8aa3b, v77
	v_exp_f32_e32 v83, v83
	v_or_b32_e32 v80, 48, v150
	v_add_f32_e32 v82, 1.0, v82
	v_rcp_f32_e32 v82, v82
	v_mad_i64_i32 v[80:81], s[52:53], v80, s70, v[140:141]
	v_lshl_add_u64 v[80:81], v[80:81], 0, v[142:143]
	v_mul_f32_e32 v76, v76, v82
	v_mul_f32_e32 v72, v72, v76
	v_add_f32_e32 v76, 1.0, v83
	v_mul_f32_e32 v82, 0xbfb8aa3b, v78
	v_rcp_f32_e32 v76, v76
	v_exp_f32_e32 v82, v82
	v_mul_f32_e32 v83, 0xbfb8aa3b, v79
	v_exp_f32_e32 v83, v83
	v_mul_f32_e32 v76, v77, v76
	v_add_f32_e32 v77, 1.0, v82
	v_rcp_f32_e32 v77, v77
	v_add_f32_e32 v82, 1.0, v83
	v_rcp_f32_e32 v82, v82
	v_mul_f32_e32 v73, v73, v76
	v_mul_f32_e32 v76, v78, v77
	v_mul_f32_e32 v77, 0xbfb8aa3b, v68
	v_exp_f32_e32 v77, v77
	v_mul_f32_e32 v74, v74, v76
	v_mul_f32_e32 v76, v79, v82
	v_mul_f32_e32 v75, v75, v76
	v_cvt_pk_bf16_f32 v72, v72, v73
	v_cvt_pk_bf16_f32 v73, v74, v75
	v_add_f32_e32 v74, 1.0, v77
	v_rcp_f32_e32 v74, v74
	v_mul_f32_e32 v75, 0xbfb8aa3b, v69
	v_exp_f32_e32 v75, v75
	global_store_dwordx2 v[80:81], v[72:73], off
	v_mul_f32_e32 v68, v68, v74
	v_mul_f32_e32 v64, v64, v68
	v_add_f32_e32 v68, 1.0, v75
	v_mul_f32_e32 v72, 0xbfb8aa3b, v70
	v_rcp_f32_e32 v68, v68
	v_exp_f32_e32 v72, v72
	v_mul_f32_e32 v73, 0xbfb8aa3b, v71
	v_exp_f32_e32 v73, v73
	v_mul_f32_e32 v68, v69, v68
	v_add_f32_e32 v69, 1.0, v72
	v_rcp_f32_e32 v69, v69
	v_add_f32_e32 v72, 1.0, v73
	v_rcp_f32_e32 v72, v72
	v_mul_f32_e32 v65, v65, v68
	v_mul_f32_e32 v68, v70, v69
	v_mul_f32_e32 v66, v66, v68
	v_mul_f32_e32 v68, v71, v72
	v_cvt_pk_bf16_f32 v64, v64, v65
	v_mul_f32_e32 v67, v67, v68
	v_cvt_pk_bf16_f32 v65, v66, v67
	global_store_dwordx2 v[80:81], v[64:65], off offset:128
	v_mul_f32_e32 v64, 0xbfb8aa3b, v60
	v_exp_f32_e32 v66, v64
	v_mul_f32_e32 v67, 0xbfb8aa3b, v61
	v_exp_f32_e32 v67, v67
	v_add_u32_e32 v64, 0x80, v150
	v_add_f32_e32 v66, 1.0, v66
	v_rcp_f32_e32 v66, v66
	v_mad_i64_i32 v[64:65], s[52:53], v64, s70, v[140:141]
	v_lshl_add_u64 v[64:65], v[64:65], 0, v[142:143]
	v_mul_f32_e32 v60, v60, v66
	v_mul_f32_e32 v56, v56, v60
	v_add_f32_e32 v60, 1.0, v67
	v_mul_f32_e32 v66, 0xbfb8aa3b, v62
	v_rcp_f32_e32 v60, v60
	v_exp_f32_e32 v66, v66
	v_mul_f32_e32 v67, 0xbfb8aa3b, v63
	v_exp_f32_e32 v67, v67
	v_mul_f32_e32 v60, v61, v60
	v_add_f32_e32 v61, 1.0, v66
	v_rcp_f32_e32 v61, v61
	v_add_f32_e32 v66, 1.0, v67
	v_rcp_f32_e32 v66, v66
	v_mul_f32_e32 v57, v57, v60
	v_mul_f32_e32 v60, v62, v61
	v_mul_f32_e32 v61, 0xbfb8aa3b, v52
	v_exp_f32_e32 v61, v61
	v_mul_f32_e32 v58, v58, v60
	v_mul_f32_e32 v60, v63, v66
	v_mul_f32_e32 v59, v59, v60
	v_cvt_pk_bf16_f32 v56, v56, v57
	v_cvt_pk_bf16_f32 v57, v58, v59
	v_add_f32_e32 v58, 1.0, v61
	v_rcp_f32_e32 v58, v58
	v_mul_f32_e32 v59, 0xbfb8aa3b, v53
	v_exp_f32_e32 v59, v59
	global_store_dwordx2 v[64:65], v[56:57], off
	v_mul_f32_e32 v52, v52, v58
	v_mul_f32_e32 v48, v48, v52
	v_add_f32_e32 v52, 1.0, v59
	v_mul_f32_e32 v56, 0xbfb8aa3b, v54
	v_rcp_f32_e32 v52, v52
	v_exp_f32_e32 v56, v56
	v_mul_f32_e32 v57, 0xbfb8aa3b, v55
	v_exp_f32_e32 v57, v57
	v_mul_f32_e32 v52, v53, v52
	v_add_f32_e32 v53, 1.0, v56
	v_rcp_f32_e32 v53, v53
	v_add_f32_e32 v56, 1.0, v57
	v_rcp_f32_e32 v56, v56
	v_mul_f32_e32 v49, v49, v52
	v_mul_f32_e32 v52, v54, v53
	v_mul_f32_e32 v50, v50, v52
	v_mul_f32_e32 v52, v55, v56
	v_cvt_pk_bf16_f32 v48, v48, v49
	v_mul_f32_e32 v51, v51, v52
	v_cvt_pk_bf16_f32 v49, v50, v51
	global_store_dwordx2 v[64:65], v[48:49], off offset:128
	v_mul_f32_e32 v48, 0xbfb8aa3b, v44
	v_exp_f32_e32 v50, v48
	v_mul_f32_e32 v51, 0xbfb8aa3b, v45
	v_exp_f32_e32 v51, v51
	v_add_u32_e32 v48, 0x90, v150
	v_add_f32_e32 v50, 1.0, v50
	v_rcp_f32_e32 v50, v50
	v_mad_i64_i32 v[48:49], s[52:53], v48, s70, v[140:141]
	v_lshl_add_u64 v[48:49], v[48:49], 0, v[142:143]
	v_mul_f32_e32 v44, v44, v50
	v_mul_f32_e32 v40, v40, v44
	v_add_f32_e32 v44, 1.0, v51
	v_mul_f32_e32 v50, 0xbfb8aa3b, v46
	v_rcp_f32_e32 v44, v44
	v_exp_f32_e32 v50, v50
	v_mul_f32_e32 v51, 0xbfb8aa3b, v47
	v_exp_f32_e32 v51, v51
	v_mul_f32_e32 v44, v45, v44
	v_add_f32_e32 v45, 1.0, v50
	v_rcp_f32_e32 v45, v45
	v_add_f32_e32 v50, 1.0, v51
	v_rcp_f32_e32 v50, v50
	v_mul_f32_e32 v41, v41, v44
	v_mul_f32_e32 v44, v46, v45
	v_mul_f32_e32 v45, 0xbfb8aa3b, v36
	v_exp_f32_e32 v45, v45
	v_mul_f32_e32 v42, v42, v44
	v_mul_f32_e32 v44, v47, v50
	v_mul_f32_e32 v43, v43, v44
	v_cvt_pk_bf16_f32 v40, v40, v41
	v_cvt_pk_bf16_f32 v41, v42, v43
	v_add_f32_e32 v42, 1.0, v45
	v_rcp_f32_e32 v42, v42
	v_mul_f32_e32 v43, 0xbfb8aa3b, v37
	v_exp_f32_e32 v43, v43
	global_store_dwordx2 v[48:49], v[40:41], off
	v_mul_f32_e32 v36, v36, v42
	v_mul_f32_e32 v32, v32, v36
	v_add_f32_e32 v36, 1.0, v43
	v_mul_f32_e32 v40, 0xbfb8aa3b, v38
	v_rcp_f32_e32 v36, v36
	v_exp_f32_e32 v40, v40
	v_mul_f32_e32 v41, 0xbfb8aa3b, v39
	v_exp_f32_e32 v41, v41
	v_mul_f32_e32 v36, v37, v36
	v_add_f32_e32 v37, 1.0, v40
	v_rcp_f32_e32 v37, v37
	v_add_f32_e32 v40, 1.0, v41
	v_rcp_f32_e32 v40, v40
	v_mul_f32_e32 v33, v33, v36
	v_mul_f32_e32 v36, v38, v37
	v_mul_f32_e32 v34, v34, v36
	v_mul_f32_e32 v36, v39, v40
	v_cvt_pk_bf16_f32 v32, v32, v33
	v_mul_f32_e32 v35, v35, v36
	v_cvt_pk_bf16_f32 v33, v34, v35
	global_store_dwordx2 v[48:49], v[32:33], off offset:128
	v_mul_f32_e32 v32, 0xbfb8aa3b, v28
	v_exp_f32_e32 v34, v32
	v_mul_f32_e32 v35, 0xbfb8aa3b, v29
	v_exp_f32_e32 v35, v35
	v_add_u32_e32 v32, 0xa0, v150
	v_add_f32_e32 v34, 1.0, v34
	v_rcp_f32_e32 v34, v34
	v_mad_i64_i32 v[32:33], s[52:53], v32, s70, v[140:141]
	v_lshl_add_u64 v[32:33], v[32:33], 0, v[142:143]
	v_mul_f32_e32 v28, v28, v34
	v_mul_f32_e32 v24, v24, v28
	v_add_f32_e32 v28, 1.0, v35
	v_mul_f32_e32 v34, 0xbfb8aa3b, v30
	v_rcp_f32_e32 v28, v28
	v_exp_f32_e32 v34, v34
	v_mul_f32_e32 v35, 0xbfb8aa3b, v31
	v_exp_f32_e32 v35, v35
	v_mul_f32_e32 v28, v29, v28
	v_add_f32_e32 v29, 1.0, v34
	v_rcp_f32_e32 v29, v29
	v_add_f32_e32 v34, 1.0, v35
	v_rcp_f32_e32 v34, v34
	v_mul_f32_e32 v25, v25, v28
	v_mul_f32_e32 v28, v30, v29
	v_mul_f32_e32 v29, 0xbfb8aa3b, v20
	v_exp_f32_e32 v29, v29
	v_mul_f32_e32 v26, v26, v28
	v_mul_f32_e32 v28, v31, v34
	v_mul_f32_e32 v27, v27, v28
	v_cvt_pk_bf16_f32 v24, v24, v25
	v_cvt_pk_bf16_f32 v25, v26, v27
	v_add_f32_e32 v26, 1.0, v29
	v_rcp_f32_e32 v26, v26
	v_mul_f32_e32 v27, 0xbfb8aa3b, v21
	v_exp_f32_e32 v27, v27
	global_store_dwordx2 v[32:33], v[24:25], off
	v_mul_f32_e32 v20, v20, v26
	v_mul_f32_e32 v16, v16, v20
	v_add_f32_e32 v20, 1.0, v27
	v_mul_f32_e32 v24, 0xbfb8aa3b, v22
	v_rcp_f32_e32 v20, v20
	v_exp_f32_e32 v24, v24
	v_mul_f32_e32 v25, 0xbfb8aa3b, v23
	v_exp_f32_e32 v25, v25
	v_mul_f32_e32 v20, v21, v20
	v_add_f32_e32 v21, 1.0, v24
	v_rcp_f32_e32 v21, v21
	v_add_f32_e32 v24, 1.0, v25
	v_rcp_f32_e32 v24, v24
	v_mul_f32_e32 v17, v17, v20
	v_mul_f32_e32 v20, v22, v21
	v_mul_f32_e32 v18, v18, v20
	v_mul_f32_e32 v20, v23, v24
	v_cvt_pk_bf16_f32 v16, v16, v17
	v_mul_f32_e32 v19, v19, v20
	v_cvt_pk_bf16_f32 v17, v18, v19
	global_store_dwordx2 v[32:33], v[16:17], off offset:128
	v_mul_f32_e32 v16, 0xbfb8aa3b, v12
	v_exp_f32_e32 v18, v16
	v_mul_f32_e32 v19, 0xbfb8aa3b, v13
	v_exp_f32_e32 v19, v19
	v_add_u32_e32 v16, 0xb0, v150
	v_add_f32_e32 v18, 1.0, v18
	v_rcp_f32_e32 v18, v18
	v_mad_i64_i32 v[16:17], s[52:53], v16, s70, v[140:141]
	v_lshl_add_u64 v[16:17], v[16:17], 0, v[142:143]
	v_mul_f32_e32 v12, v12, v18
	v_mul_f32_e32 v8, v8, v12
	v_add_f32_e32 v12, 1.0, v19
	v_mul_f32_e32 v18, 0xbfb8aa3b, v14
	v_rcp_f32_e32 v12, v12
	v_exp_f32_e32 v18, v18
	v_mul_f32_e32 v19, 0xbfb8aa3b, v15
	v_exp_f32_e32 v19, v19
	v_mul_f32_e32 v12, v13, v12
	v_add_f32_e32 v13, 1.0, v18
	v_rcp_f32_e32 v13, v13
	v_add_f32_e32 v18, 1.0, v19
	v_rcp_f32_e32 v18, v18
	v_mul_f32_e32 v9, v9, v12
	v_mul_f32_e32 v12, v14, v13
	v_mul_f32_e32 v13, 0xbfb8aa3b, v4
	v_exp_f32_e32 v13, v13
	v_mul_f32_e32 v10, v10, v12
	v_mul_f32_e32 v12, v15, v18
	v_mul_f32_e32 v11, v11, v12
	v_cvt_pk_bf16_f32 v8, v8, v9
	v_cvt_pk_bf16_f32 v9, v10, v11
	v_add_f32_e32 v10, 1.0, v13
	v_rcp_f32_e32 v10, v10
	v_mul_f32_e32 v11, 0xbfb8aa3b, v5
	v_exp_f32_e32 v11, v11
	global_store_dwordx2 v[16:17], v[8:9], off
	v_mul_f32_e32 v4, v4, v10
	v_mul_f32_e32 v0, v0, v4
	v_add_f32_e32 v4, 1.0, v11
	v_mul_f32_e32 v8, 0xbfb8aa3b, v6
	v_rcp_f32_e32 v4, v4
	v_exp_f32_e32 v8, v8
	v_mul_f32_e32 v9, 0xbfb8aa3b, v7
	v_exp_f32_e32 v9, v9
	v_mul_f32_e32 v4, v5, v4
	v_add_f32_e32 v5, 1.0, v8
	v_rcp_f32_e32 v5, v5
	v_add_f32_e32 v8, 1.0, v9
	v_rcp_f32_e32 v8, v8
	v_mul_f32_e32 v1, v1, v4
	v_mul_f32_e32 v4, v6, v5
	v_mul_f32_e32 v2, v2, v4
	v_mul_f32_e32 v4, v7, v8
	s_andn2_b64 vcc, exec, s[10:11]
	s_mov_b64 s[10:11], -1
	v_mul_f32_e32 v3, v3, v4
	v_cvt_pk_bf16_f32 v0, v0, v1
	v_cvt_pk_bf16_f32 v1, v2, v3
	global_store_dwordx2 v[16:17], v[0:1], off offset:128
	s_cbranch_vccnz .LBB0_947
	s_andn2_b64 vcc, exec, s[0:1]
	s_cbranch_vccnz .LBB0_946
	s_barrier
	s_branch .LBB0_946

.LBB0_1034:
	v_lshl_add_u32 v152, s84, 8, v146
	v_lshl_or_b32 v144, s85, 8, v148
	v_ashrrev_i32_e32 v145, 31, v144
	v_ashrrev_i32_e32 v153, 31, v152
	v_lshl_add_u64 v[154:155], v[144:145], 1, s[24:25]
	v_lshlrev_b64 v[144:145], 11, v[152:153]
	v_lshl_add_u64 v[144:145], v[154:155], 0, v[144:145]
	s_nop 15
	s_nop 7
	v_cvt_pk_bf16_f32 v124, v124, v125
	v_cvt_pk_bf16_f32 v125, v126, v127
	v_cvt_pk_bf16_f32 v126, v120, v121
	v_cvt_pk_bf16_f32 v127, v122, v123
	global_store_dwordx4 v[144:145], v[124:127], off
	v_cvt_pk_bf16_f32 v112, v112, v113
	v_cvt_pk_bf16_f32 v113, v114, v115
	v_cvt_pk_bf16_f32 v114, v104, v105
	v_or_b32_e32 v104, 16, v152
	v_ashrrev_i32_e32 v105, 31, v104
	v_lshlrev_b64 v[104:105], 11, v[104:105]
	v_cvt_pk_bf16_f32 v115, v106, v107
	global_store_dwordx4 v[144:145], v[112:115], off offset:256
	s_nop 1
	v_lshl_add_u64 v[112:113], v[154:155], 0, v[104:105]
	v_cvt_pk_bf16_f32 v104, v116, v117
	v_cvt_pk_bf16_f32 v105, v118, v119
	v_cvt_pk_bf16_f32 v106, v108, v109
	v_cvt_pk_bf16_f32 v107, v110, v111
	global_store_dwordx4 v[112:113], v[104:107], off
	v_cvt_pk_bf16_f32 v96, v96, v97
	v_cvt_pk_bf16_f32 v97, v98, v99
	v_cvt_pk_bf16_f32 v98, v88, v89
	v_or_b32_e32 v88, 32, v152
	v_ashrrev_i32_e32 v89, 31, v88
	v_lshlrev_b64 v[88:89], 11, v[88:89]
	v_cvt_pk_bf16_f32 v99, v90, v91
	global_store_dwordx4 v[112:113], v[96:99], off offset:256
	s_nop 1
	v_lshl_add_u64 v[96:97], v[154:155], 0, v[88:89]
	v_cvt_pk_bf16_f32 v88, v100, v101
	v_cvt_pk_bf16_f32 v89, v102, v103
	v_cvt_pk_bf16_f32 v90, v92, v93
	v_cvt_pk_bf16_f32 v91, v94, v95
	global_store_dwordx4 v[96:97], v[88:91], off
	v_cvt_pk_bf16_f32 v80, v80, v81
	v_cvt_pk_bf16_f32 v81, v82, v83
	v_cvt_pk_bf16_f32 v82, v72, v73
	v_or_b32_e32 v72, 48, v152
	s_and_b64 vcc, exec, s[18:19]
	s_cbranch_vccz .Lxb_8
	s_barrier
.Lxb_8:
	v_ashrrev_i32_e32 v73, 31, v72
	v_lshlrev_b64 v[72:73], 11, v[72:73]
	v_cvt_pk_bf16_f32 v83, v74, v75
	global_store_dwordx4 v[96:97], v[80:83], off offset:256
	s_nop 1
	v_lshl_add_u64 v[80:81], v[154:155], 0, v[72:73]
	v_cvt_pk_bf16_f32 v72, v84, v85
	v_cvt_pk_bf16_f32 v73, v86, v87
	v_cvt_pk_bf16_f32 v74, v76, v77
	v_cvt_pk_bf16_f32 v75, v78, v79
	global_store_dwordx4 v[80:81], v[72:75], off
	v_cvt_pk_bf16_f32 v68, v68, v69
	v_cvt_pk_bf16_f32 v69, v70, v71
	v_cvt_pk_bf16_f32 v70, v64, v65
	v_cvt_pk_bf16_f32 v71, v66, v67
	global_store_dwordx4 v[80:81], v[68:71], off offset:256
	v_cvt_pk_bf16_f32 v60, v60, v61
	v_cvt_pk_bf16_f32 v61, v62, v63
	v_cvt_pk_bf16_f32 v62, v56, v57
	v_add_co_u32_e32 v56, vcc, s74, v144
	v_lshl_add_u64 v[64:65], v[144:145], 0, s[36:37]
	s_nop 0
	v_addc_co_u32_e32 v57, vcc, 0, v145, vcc
	v_cvt_pk_bf16_f32 v63, v58, v59
	global_store_dwordx4 v[56:57], v[60:63], off
	v_cvt_pk_bf16_f32 v48, v48, v49
	v_cvt_pk_bf16_f32 v49, v50, v51
	v_cvt_pk_bf16_f32 v50, v40, v41
	v_cvt_pk_bf16_f32 v51, v42, v43
	global_store_dwordx4 v[64:65], v[48:51], off offset:256
	v_cvt_pk_bf16_f32 v40, v52, v53
	v_cvt_pk_bf16_f32 v41, v54, v55
	v_cvt_pk_bf16_f32 v42, v44, v45
	v_add_co_u32_e32 v44, vcc, s75, v144
	s_nop 0
	v_lshl_add_u64 v[48:49], v[144:145], 0, s[44:45]
	v_addc_co_u32_e32 v45, vcc, 0, v145, vcc
	v_cvt_pk_bf16_f32 v43, v46, v47
	global_store_dwordx4 v[44:45], v[40:43], off
	v_cvt_pk_bf16_f32 v32, v32, v33
	v_cvt_pk_bf16_f32 v33, v34, v35
	v_cvt_pk_bf16_f32 v34, v24, v25
	v_cvt_pk_bf16_f32 v35, v26, v27
	global_store_dwordx4 v[48:49], v[32:35], off offset:256
	v_cvt_pk_bf16_f32 v24, v36, v37
	v_cvt_pk_bf16_f32 v25, v38, v39
	v_cvt_pk_bf16_f32 v26, v28, v29
	v_add_co_u32_e32 v28, vcc, s76, v144
	s_nop 0
	v_lshl_add_u64 v[32:33], v[144:145], 0, s[46:47]
	v_addc_co_u32_e32 v29, vcc, 0, v145, vcc
	v_cvt_pk_bf16_f32 v27, v30, v31
	global_store_dwordx4 v[28:29], v[24:27], off
	v_cvt_pk_bf16_f32 v16, v16, v17
	v_cvt_pk_bf16_f32 v17, v18, v19
	v_cvt_pk_bf16_f32 v18, v8, v9
	v_cvt_pk_bf16_f32 v19, v10, v11
	global_store_dwordx4 v[32:33], v[16:19], off offset:256
	v_cvt_pk_bf16_f32 v8, v20, v21
	v_cvt_pk_bf16_f32 v9, v22, v23
	v_cvt_pk_bf16_f32 v10, v12, v13
	v_add_co_u32_e32 v12, vcc, s77, v144
	s_nop 0
	v_lshl_add_u64 v[16:17], v[144:145], 0, s[48:49]
	v_addc_co_u32_e32 v13, vcc, 0, v145, vcc
	s_and_b64 vcc, exec, s[10:11]
	s_mov_b64 s[10:11], -1
	v_cvt_pk_bf16_f32 v11, v14, v15
	global_store_dwordx4 v[12:13], v[8:11], off
	v_cvt_pk_bf16_f32 v4, v4, v5
	v_cvt_pk_bf16_f32 v5, v6, v7
	v_cvt_pk_bf16_f32 v6, v0, v1
	v_cvt_pk_bf16_f32 v7, v2, v3
	global_store_dwordx4 v[16:17], v[4:7], off offset:256
	s_cbranch_vccnz .LBB0_1019
	s_andn2_b64 vcc, exec, s[0:1]
	s_cbranch_vccnz .LBB0_1018
	s_barrier
	s_branch .LBB0_1018

.LBB0_1165:
	s_lshl_b32 s49, s59, 8
	s_or_b32 s49, s49, s74
	v_lshl_add_u32 v152, s58, 8, v146
	s_ashr_i32 s58, s49, 6
	s_ashr_i32 s59, s58, 31
	s_lshl_b64 s[60:61], s[58:59], 22
	s_cmp_lt_i32 s58, 16
	s_cselect_b64 vcc, -1, 0
	v_cndmask_b32_e32 v156, 1.0, v151, vcc
	v_pk_mul_f32 v[124:125], v[156:157], v[124:125] op_sel_hi:[0,1]
	v_ashrrev_i32_e32 v153, 31, v152
	v_lshl_add_u64 v[154:155], v[136:137], 0, s[60:61]
	v_pk_mul_f32 v[126:127], v[156:157], v[126:127] op_sel_hi:[0,1]
	v_pk_mul_f32 v[158:159], v[156:157], v[122:123] op_sel_hi:[0,1]
	v_pk_mul_f32 v[122:123], v[156:157], v[120:121] op_sel_hi:[0,1]
	v_cvt_pk_bf16_f32 v120, v124, v125
	v_lshlrev_b64 v[124:125], 7, v[152:153]
	v_cvt_pk_bf16_f32 v121, v126, v127
	v_lshl_add_u64 v[126:127], v[154:155], 0, v[124:125]
	v_pk_mul_f32 v[116:117], v[156:157], v[116:117] op_sel_hi:[0,1]
	v_cvt_pk_bf16_f32 v122, v122, v123
	v_cvt_pk_bf16_f32 v123, v158, v159
	global_store_dwordx4 v[126:127], v[120:123], off
	v_pk_mul_f32 v[118:119], v[156:157], v[118:119] op_sel_hi:[0,1]
	v_pk_mul_f32 v[108:109], v[156:157], v[108:109] op_sel_hi:[0,1]
	v_pk_mul_f32 v[120:121], v[156:157], v[114:115] op_sel_hi:[0,1]
	v_pk_mul_f32 v[114:115], v[156:157], v[112:113] op_sel_hi:[0,1]
	v_cvt_pk_bf16_f32 v112, v116, v117
	v_or_b32_e32 v116, 16, v152
	v_ashrrev_i32_e32 v117, 31, v116
	v_lshlrev_b64 v[116:117], 7, v[116:117]
	v_cvt_pk_bf16_f32 v113, v118, v119
	v_lshl_add_u64 v[118:119], v[154:155], 0, v[116:117]
	v_cvt_pk_bf16_f32 v114, v114, v115
	v_cvt_pk_bf16_f32 v115, v120, v121
	global_store_dwordx4 v[118:119], v[112:115], off
	v_pk_mul_f32 v[110:111], v[156:157], v[110:111] op_sel_hi:[0,1]
	v_pk_mul_f32 v[100:101], v[156:157], v[100:101] op_sel_hi:[0,1]
	v_pk_mul_f32 v[112:113], v[156:157], v[106:107] op_sel_hi:[0,1]
	v_pk_mul_f32 v[106:107], v[156:157], v[104:105] op_sel_hi:[0,1]
	v_cvt_pk_bf16_f32 v104, v108, v109
	v_or_b32_e32 v108, 32, v152
	v_ashrrev_i32_e32 v109, 31, v108
	v_lshlrev_b64 v[108:109], 7, v[108:109]
	v_cvt_pk_bf16_f32 v105, v110, v111
	v_lshl_add_u64 v[110:111], v[154:155], 0, v[108:109]
	v_cvt_pk_bf16_f32 v106, v106, v107
	v_cvt_pk_bf16_f32 v107, v112, v113
	s_and_b64 vcc, exec, s[16:17]
	s_cbranch_vccz .Lxb_9
	s_barrier
.Lxb_9:
	global_store_dwordx4 v[110:111], v[104:107], off
	v_pk_mul_f32 v[102:103], v[156:157], v[102:103] op_sel_hi:[0,1]
	v_pk_mul_f32 v[92:93], v[156:157], v[92:93] op_sel_hi:[0,1]
	v_pk_mul_f32 v[104:105], v[156:157], v[98:99] op_sel_hi:[0,1]
	v_pk_mul_f32 v[98:99], v[156:157], v[96:97] op_sel_hi:[0,1]
	v_cvt_pk_bf16_f32 v96, v100, v101
	v_or_b32_e32 v100, 48, v152
	v_ashrrev_i32_e32 v101, 31, v100
	v_lshlrev_b64 v[100:101], 7, v[100:101]
	v_cvt_pk_bf16_f32 v97, v102, v103
	v_lshl_add_u64 v[102:103], v[154:155], 0, v[100:101]
	v_cvt_pk_bf16_f32 v98, v98, v99
	v_cvt_pk_bf16_f32 v99, v104, v105
	global_store_dwordx4 v[102:103], v[96:99], off
	v_pk_mul_f32 v[94:95], v[156:157], v[94:95] op_sel_hi:[0,1]
	v_pk_mul_f32 v[84:85], v[156:157], v[84:85] op_sel_hi:[0,1]
	v_pk_mul_f32 v[96:97], v[156:157], v[90:91] op_sel_hi:[0,1]
	v_pk_mul_f32 v[90:91], v[156:157], v[88:89] op_sel_hi:[0,1]
	v_cvt_pk_bf16_f32 v88, v92, v93
	v_lshl_add_u64 v[92:93], v[124:125], 0, s[18:19]
	v_cvt_pk_bf16_f32 v89, v94, v95
	v_lshl_add_u64 v[94:95], v[154:155], 0, v[92:93]
	v_cvt_pk_bf16_f32 v90, v90, v91
	v_cvt_pk_bf16_f32 v91, v96, v97
	global_store_dwordx4 v[94:95], v[88:91], off
	v_pk_mul_f32 v[86:87], v[156:157], v[86:87] op_sel_hi:[0,1]
	s_or_b32 s58, s58, 2
	v_pk_mul_f32 v[88:89], v[156:157], v[82:83] op_sel_hi:[0,1]
	v_pk_mul_f32 v[82:83], v[156:157], v[80:81] op_sel_hi:[0,1]
	v_cvt_pk_bf16_f32 v80, v84, v85
	v_lshl_add_u64 v[84:85], v[124:125], 0, s[36:37]
	v_cvt_pk_bf16_f32 v81, v86, v87
	v_lshl_add_u64 v[86:87], v[154:155], 0, v[84:85]
	v_pk_mul_f32 v[76:77], v[156:157], v[76:77] op_sel_hi:[0,1]
	s_ashr_i32 s59, s58, 31
	v_cvt_pk_bf16_f32 v82, v82, v83
	v_cvt_pk_bf16_f32 v83, v88, v89
	global_store_dwordx4 v[86:87], v[80:83], off
	v_pk_mul_f32 v[78:79], v[156:157], v[78:79] op_sel_hi:[0,1]
	s_lshl_b64 s[60:61], s[58:59], 22
	v_pk_mul_f32 v[80:81], v[156:157], v[74:75] op_sel_hi:[0,1]
	v_pk_mul_f32 v[74:75], v[156:157], v[72:73] op_sel_hi:[0,1]
	v_cvt_pk_bf16_f32 v72, v76, v77
	v_lshl_add_u64 v[76:77], v[124:125], 0, s[44:45]
	v_cvt_pk_bf16_f32 v73, v78, v79
	v_lshl_add_u64 v[78:79], v[154:155], 0, v[76:77]
	v_pk_mul_f32 v[60:61], v[156:157], v[60:61] op_sel_hi:[0,1]
	s_cmp_lt_i32 s58, 16
	v_cvt_pk_bf16_f32 v74, v74, v75
	v_cvt_pk_bf16_f32 v75, v80, v81
	global_store_dwordx4 v[78:79], v[72:75], off
	v_pk_mul_f32 v[62:63], v[156:157], v[62:63] op_sel_hi:[0,1]
	s_cselect_b64 vcc, -1, 0
	v_pk_mul_f32 v[72:73], v[156:157], v[58:59] op_sel_hi:[0,1]
	v_pk_mul_f32 v[58:59], v[156:157], v[56:57] op_sel_hi:[0,1]
	v_cvt_pk_bf16_f32 v56, v60, v61
	v_lshl_add_u64 v[60:61], v[124:125], 0, s[46:47]
	v_cvt_pk_bf16_f32 v57, v62, v63
	v_cvt_pk_bf16_f32 v58, v58, v59
	v_cvt_pk_bf16_f32 v59, v72, v73
	v_lshl_add_u64 v[62:63], v[154:155], 0, v[60:61]
	v_cndmask_b32_e32 v72, 1.0, v151, vcc
	global_store_dwordx4 v[62:63], v[56:59], off
	v_lshl_add_u64 v[62:63], v[136:137], 0, s[60:61]
	v_pk_mul_f32 v[64:65], v[72:73], v[64:65] op_sel_hi:[0,1]
	v_pk_mul_f32 v[58:59], v[72:73], v[70:71] op_sel_hi:[0,1]
	v_pk_mul_f32 v[56:57], v[72:73], v[68:69] op_sel_hi:[0,1]
	v_cvt_pk_bf16_f32 v56, v56, v57
	v_cvt_pk_bf16_f32 v57, v58, v59
	v_cvt_pk_bf16_f32 v58, v64, v65
	v_lshl_add_u64 v[64:65], v[62:63], 0, v[124:125]
	v_pk_mul_f32 v[52:53], v[72:73], v[52:53] op_sel_hi:[0,1]
	v_pk_mul_f32 v[66:67], v[72:73], v[66:67] op_sel_hi:[0,1]
	v_cvt_pk_bf16_f32 v59, v66, v67
	global_store_dwordx4 v[64:65], v[56:59], off
	v_pk_mul_f32 v[54:55], v[72:73], v[54:55] op_sel_hi:[0,1]
	v_pk_mul_f32 v[44:45], v[72:73], v[44:45] op_sel_hi:[0,1]
	v_pk_mul_f32 v[56:57], v[72:73], v[50:51] op_sel_hi:[0,1]
	v_pk_mul_f32 v[50:51], v[72:73], v[48:49] op_sel_hi:[0,1]
	v_cvt_pk_bf16_f32 v48, v52, v53
	v_cvt_pk_bf16_f32 v49, v54, v55
	v_lshl_add_u64 v[52:53], v[62:63], 0, v[116:117]
	v_cvt_pk_bf16_f32 v50, v50, v51
	v_cvt_pk_bf16_f32 v51, v56, v57
	global_store_dwordx4 v[52:53], v[48:51], off
	v_pk_mul_f32 v[46:47], v[72:73], v[46:47] op_sel_hi:[0,1]
	v_pk_mul_f32 v[36:37], v[72:73], v[36:37] op_sel_hi:[0,1]
	v_pk_mul_f32 v[48:49], v[72:73], v[42:43] op_sel_hi:[0,1]
	v_pk_mul_f32 v[42:43], v[72:73], v[40:41] op_sel_hi:[0,1]
	v_cvt_pk_bf16_f32 v40, v44, v45
	v_cvt_pk_bf16_f32 v41, v46, v47
	v_lshl_add_u64 v[44:45], v[62:63], 0, v[108:109]
	v_cvt_pk_bf16_f32 v42, v42, v43
	v_cvt_pk_bf16_f32 v43, v48, v49
	global_store_dwordx4 v[44:45], v[40:43], off
	v_pk_mul_f32 v[38:39], v[72:73], v[38:39] op_sel_hi:[0,1]
	v_pk_mul_f32 v[28:29], v[72:73], v[28:29] op_sel_hi:[0,1]
	v_pk_mul_f32 v[40:41], v[72:73], v[34:35] op_sel_hi:[0,1]
	v_pk_mul_f32 v[34:35], v[72:73], v[32:33] op_sel_hi:[0,1]
	v_cvt_pk_bf16_f32 v32, v36, v37
	v_cvt_pk_bf16_f32 v33, v38, v39
	v_lshl_add_u64 v[36:37], v[62:63], 0, v[100:101]
	v_cvt_pk_bf16_f32 v34, v34, v35
	v_cvt_pk_bf16_f32 v35, v40, v41
	global_store_dwordx4 v[36:37], v[32:35], off
	v_pk_mul_f32 v[30:31], v[72:73], v[30:31] op_sel_hi:[0,1]
	v_pk_mul_f32 v[20:21], v[72:73], v[20:21] op_sel_hi:[0,1]
	v_pk_mul_f32 v[32:33], v[72:73], v[26:27] op_sel_hi:[0,1]
	v_pk_mul_f32 v[26:27], v[72:73], v[24:25] op_sel_hi:[0,1]
	v_cvt_pk_bf16_f32 v24, v28, v29
	v_cvt_pk_bf16_f32 v25, v30, v31
	v_lshl_add_u64 v[28:29], v[62:63], 0, v[92:93]
	v_cvt_pk_bf16_f32 v26, v26, v27
	v_cvt_pk_bf16_f32 v27, v32, v33
	global_store_dwordx4 v[28:29], v[24:27], off
	v_pk_mul_f32 v[22:23], v[72:73], v[22:23] op_sel_hi:[0,1]
	v_pk_mul_f32 v[12:13], v[72:73], v[12:13] op_sel_hi:[0,1]
	v_pk_mul_f32 v[24:25], v[72:73], v[18:19] op_sel_hi:[0,1]
	v_pk_mul_f32 v[18:19], v[72:73], v[16:17] op_sel_hi:[0,1]
	v_cvt_pk_bf16_f32 v16, v20, v21
	v_cvt_pk_bf16_f32 v17, v22, v23
	v_lshl_add_u64 v[20:21], v[62:63], 0, v[84:85]
	v_cvt_pk_bf16_f32 v18, v18, v19
	v_cvt_pk_bf16_f32 v19, v24, v25
	global_store_dwordx4 v[20:21], v[16:19], off
	v_pk_mul_f32 v[14:15], v[72:73], v[14:15] op_sel_hi:[0,1]
	v_pk_mul_f32 v[4:5], v[72:73], v[4:5] op_sel_hi:[0,1]
	v_pk_mul_f32 v[16:17], v[72:73], v[10:11] op_sel_hi:[0,1]
	v_pk_mul_f32 v[10:11], v[72:73], v[8:9] op_sel_hi:[0,1]
	v_cvt_pk_bf16_f32 v8, v12, v13
	v_cvt_pk_bf16_f32 v9, v14, v15
	v_lshl_add_u64 v[12:13], v[62:63], 0, v[76:77]
	v_cvt_pk_bf16_f32 v10, v10, v11
	v_cvt_pk_bf16_f32 v11, v16, v17
	global_store_dwordx4 v[12:13], v[8:11], off
	s_andn2_b64 vcc, exec, s[10:11]
	s_mov_b64 s[10:11], -1
	v_pk_mul_f32 v[8:9], v[72:73], v[2:3] op_sel_hi:[0,1]
	v_pk_mul_f32 v[2:3], v[72:73], v[0:1] op_sel_hi:[0,1]
	v_cvt_pk_bf16_f32 v0, v4, v5
	v_lshl_add_u64 v[4:5], v[62:63], 0, v[60:61]
	v_pk_mul_f32 v[6:7], v[72:73], v[6:7] op_sel_hi:[0,1]
	v_cvt_pk_bf16_f32 v1, v6, v7
	v_cvt_pk_bf16_f32 v2, v2, v3
	v_cvt_pk_bf16_f32 v3, v8, v9
	global_store_dwordx4 v[4:5], v[0:3], off
	s_cbranch_vccnz .LBB0_1154
	s_andn2_b64 vcc, exec, s[0:1]
	s_cbranch_vccnz .LBB0_1153
	s_barrier
	s_branch .LBB0_1153

.LBB0_1314:
	v_lshl_add_u32 v152, s54, 8, v146
	v_lshl_or_b32 v144, s77, 8, v148
	v_ashrrev_i32_e32 v145, 31, v144
	v_ashrrev_i32_e32 v153, 31, v152
	v_lshl_add_u64 v[154:155], v[144:145], 1, s[24:25]
	v_lshlrev_b64 v[144:145], 11, v[152:153]
	v_lshl_add_u64 v[144:145], v[154:155], 0, v[144:145]
	s_nop 15
	s_nop 7
	v_cvt_pk_bf16_f32 v124, v124, v125
	v_cvt_pk_bf16_f32 v125, v126, v127
	v_cvt_pk_bf16_f32 v126, v120, v121
	v_cvt_pk_bf16_f32 v127, v122, v123
	global_store_dwordx4 v[144:145], v[124:127], off
	v_cvt_pk_bf16_f32 v112, v112, v113
	v_cvt_pk_bf16_f32 v113, v114, v115
	v_cvt_pk_bf16_f32 v114, v104, v105
	v_or_b32_e32 v104, 16, v152
	v_ashrrev_i32_e32 v105, 31, v104
	v_lshlrev_b64 v[104:105], 11, v[104:105]
	v_cvt_pk_bf16_f32 v115, v106, v107
	global_store_dwordx4 v[144:145], v[112:115], off offset:256
	s_nop 1
	v_lshl_add_u64 v[112:113], v[154:155], 0, v[104:105]
	v_cvt_pk_bf16_f32 v104, v116, v117
	v_cvt_pk_bf16_f32 v105, v118, v119
	v_cvt_pk_bf16_f32 v106, v108, v109
	v_cvt_pk_bf16_f32 v107, v110, v111
	global_store_dwordx4 v[112:113], v[104:107], off
	v_cvt_pk_bf16_f32 v96, v96, v97
	v_cvt_pk_bf16_f32 v97, v98, v99
	v_cvt_pk_bf16_f32 v98, v88, v89
	v_or_b32_e32 v88, 32, v152
	v_ashrrev_i32_e32 v89, 31, v88
	v_lshlrev_b64 v[88:89], 11, v[88:89]
	v_cvt_pk_bf16_f32 v99, v90, v91
	global_store_dwordx4 v[112:113], v[96:99], off offset:256
	s_nop 1
	v_lshl_add_u64 v[96:97], v[154:155], 0, v[88:89]
	v_cvt_pk_bf16_f32 v88, v100, v101
	v_cvt_pk_bf16_f32 v89, v102, v103
	v_cvt_pk_bf16_f32 v90, v92, v93
	v_cvt_pk_bf16_f32 v91, v94, v95
	global_store_dwordx4 v[96:97], v[88:91], off
	v_cvt_pk_bf16_f32 v80, v80, v81
	v_cvt_pk_bf16_f32 v81, v82, v83
	v_cvt_pk_bf16_f32 v82, v72, v73
	v_or_b32_e32 v72, 48, v152
	s_and_b64 vcc, exec, s[18:19]
	s_cbranch_vccz .Lxb_10
	s_barrier
.Lxb_10:
	v_ashrrev_i32_e32 v73, 31, v72
	v_lshlrev_b64 v[72:73], 11, v[72:73]
	v_cvt_pk_bf16_f32 v83, v74, v75
	global_store_dwordx4 v[96:97], v[80:83], off offset:256
	s_nop 1
	v_lshl_add_u64 v[80:81], v[154:155], 0, v[72:73]
	v_cvt_pk_bf16_f32 v72, v84, v85
	v_cvt_pk_bf16_f32 v73, v86, v87
	v_cvt_pk_bf16_f32 v74, v76, v77
	v_cvt_pk_bf16_f32 v75, v78, v79
	global_store_dwordx4 v[80:81], v[72:75], off
	v_cvt_pk_bf16_f32 v68, v68, v69
	v_cvt_pk_bf16_f32 v69, v70, v71
	v_cvt_pk_bf16_f32 v70, v64, v65
	v_cvt_pk_bf16_f32 v71, v66, v67
	global_store_dwordx4 v[80:81], v[68:71], off offset:256
	v_cvt_pk_bf16_f32 v60, v60, v61
	v_cvt_pk_bf16_f32 v61, v62, v63
	v_cvt_pk_bf16_f32 v62, v56, v57
	v_add_co_u32_e32 v56, vcc, s73, v144
	v_lshl_add_u64 v[64:65], v[144:145], 0, s[0:1]
	s_nop 0
	v_addc_co_u32_e32 v57, vcc, 0, v145, vcc
	v_cvt_pk_bf16_f32 v63, v58, v59
	global_store_dwordx4 v[56:57], v[60:63], off
	v_cvt_pk_bf16_f32 v48, v48, v49
	v_cvt_pk_bf16_f32 v49, v50, v51
	v_cvt_pk_bf16_f32 v50, v40, v41
	v_cvt_pk_bf16_f32 v51, v42, v43
	global_store_dwordx4 v[64:65], v[48:51], off offset:256
	v_cvt_pk_bf16_f32 v40, v52, v53
	v_cvt_pk_bf16_f32 v41, v54, v55
	v_cvt_pk_bf16_f32 v42, v44, v45
	v_add_co_u32_e32 v44, vcc, s74, v144
	s_nop 0
	v_lshl_add_u64 v[48:49], v[144:145], 0, s[30:31]
	v_addc_co_u32_e32 v45, vcc, 0, v145, vcc
	v_cvt_pk_bf16_f32 v43, v46, v47
	global_store_dwordx4 v[44:45], v[40:43], off
	v_cvt_pk_bf16_f32 v32, v32, v33
	v_cvt_pk_bf16_f32 v33, v34, v35
	v_cvt_pk_bf16_f32 v34, v24, v25
	v_cvt_pk_bf16_f32 v35, v26, v27
	global_store_dwordx4 v[48:49], v[32:35], off offset:256
	v_cvt_pk_bf16_f32 v24, v36, v37
	v_cvt_pk_bf16_f32 v25, v38, v39
	v_cvt_pk_bf16_f32 v26, v28, v29
	v_add_co_u32_e32 v28, vcc, s75, v144
	s_nop 0
	v_lshl_add_u64 v[32:33], v[144:145], 0, s[36:37]
	v_addc_co_u32_e32 v29, vcc, 0, v145, vcc
	v_cvt_pk_bf16_f32 v27, v30, v31
	global_store_dwordx4 v[28:29], v[24:27], off
	v_cvt_pk_bf16_f32 v16, v16, v17
	v_cvt_pk_bf16_f32 v17, v18, v19
	v_cvt_pk_bf16_f32 v18, v8, v9
	v_cvt_pk_bf16_f32 v19, v10, v11
	global_store_dwordx4 v[32:33], v[16:19], off offset:256
	v_cvt_pk_bf16_f32 v8, v20, v21
	v_cvt_pk_bf16_f32 v9, v22, v23
	v_cvt_pk_bf16_f32 v10, v12, v13
	v_add_co_u32_e32 v12, vcc, s76, v144
	s_nop 0
	v_lshl_add_u64 v[16:17], v[144:145], 0, s[44:45]
	v_addc_co_u32_e32 v13, vcc, 0, v145, vcc
	s_andn2_b64 vcc, exec, s[10:11]
	s_mov_b64 s[10:11], -1
	v_cvt_pk_bf16_f32 v11, v14, v15
	global_store_dwordx4 v[12:13], v[8:11], off
	v_cvt_pk_bf16_f32 v4, v4, v5
	v_cvt_pk_bf16_f32 v5, v6, v7
	v_cvt_pk_bf16_f32 v6, v0, v1
	v_cvt_pk_bf16_f32 v7, v2, v3
	global_store_dwordx4 v[16:17], v[4:7], off offset:256
	s_cbranch_vccnz .LBB0_1303
	s_andn2_b64 vcc, exec, s[12:13]
	s_cbranch_vccnz .LBB0_1302
	s_barrier
	s_branch .LBB0_1302

.LBB0_1437:
	v_mul_f32_e32 v151, 0xbfb8aa3b, v124
	v_exp_f32_e32 v151, v151
	v_mul_f32_e32 v154, 0xbfb8aa3b, v125
	v_exp_f32_e32 v154, v154
	v_lshl_or_b32 v142, s65, 7, v146
	v_add_f32_e32 v151, 1.0, v151
	v_rcp_f32_e32 v151, v151
	v_lshl_add_u32 v150, s44, 8, v144
	v_ashrrev_i32_e32 v143, 31, v142
	v_mov_b64_e32 v[140:141], s[22:23]
	v_mul_f32_e32 v124, v124, v151
	v_mul_f32_e32 v120, v120, v124
	v_add_f32_e32 v124, 1.0, v154
	v_mul_f32_e32 v151, 0xbfb8aa3b, v126
	v_rcp_f32_e32 v124, v124
	v_exp_f32_e32 v151, v151
	v_mul_f32_e32 v154, 0xbfb8aa3b, v127
	v_exp_f32_e32 v154, v154
	v_mul_f32_e32 v124, v125, v124
	v_add_f32_e32 v125, 1.0, v151
	v_rcp_f32_e32 v125, v125
	v_add_f32_e32 v151, 1.0, v154
	v_rcp_f32_e32 v151, v151
	v_mul_f32_e32 v121, v121, v124
	v_mul_f32_e32 v124, v126, v125
	v_mul_f32_e32 v125, 0xbfb8aa3b, v116
	v_exp_f32_e32 v125, v125
	v_mul_f32_e32 v122, v122, v124
	v_mul_f32_e32 v124, v127, v151
	v_mul_f32_e32 v123, v123, v124
	v_cvt_pk_bf16_f32 v120, v120, v121
	v_cvt_pk_bf16_f32 v121, v122, v123
	v_add_f32_e32 v122, 1.0, v125
	v_rcp_f32_e32 v122, v122
	v_mul_f32_e32 v123, 0xbfb8aa3b, v117
	v_exp_f32_e32 v123, v123
	v_mad_i64_i32 v[152:153], s[46:47], v150, s64, v[140:141]
	v_lshlrev_b64 v[142:143], 1, v[142:143]
	v_lshl_add_u64 v[152:153], v[152:153], 0, v[142:143]
	v_mul_f32_e32 v116, v116, v122
	global_store_dwordx2 v[152:153], v[120:121], off
	v_mul_f32_e32 v112, v112, v116
	v_add_f32_e32 v116, 1.0, v123
	v_mul_f32_e32 v120, 0xbfb8aa3b, v118
	v_rcp_f32_e32 v116, v116
	v_exp_f32_e32 v120, v120
	v_mul_f32_e32 v121, 0xbfb8aa3b, v119
	v_exp_f32_e32 v121, v121
	v_mul_f32_e32 v116, v117, v116
	v_add_f32_e32 v117, 1.0, v120
	v_rcp_f32_e32 v117, v117
	v_add_f32_e32 v120, 1.0, v121
	v_rcp_f32_e32 v120, v120
	v_mul_f32_e32 v113, v113, v116
	v_mul_f32_e32 v116, v118, v117
	v_mul_f32_e32 v114, v114, v116
	v_mul_f32_e32 v116, v119, v120
	v_cvt_pk_bf16_f32 v112, v112, v113
	v_mul_f32_e32 v115, v115, v116
	v_cvt_pk_bf16_f32 v113, v114, v115
	global_store_dwordx2 v[152:153], v[112:113], off offset:128
	v_mul_f32_e32 v112, 0xbfb8aa3b, v108
	v_exp_f32_e32 v114, v112
	v_mul_f32_e32 v115, 0xbfb8aa3b, v109
	s_and_b64 vcc, exec, s[12:13]
	s_cbranch_vccz .Lxb_11
	s_barrier
.Lxb_11:
	v_exp_f32_e32 v115, v115
	v_or_b32_e32 v112, 16, v150
	v_add_f32_e32 v114, 1.0, v114
	v_rcp_f32_e32 v114, v114
	v_mad_i64_i32 v[112:113], s[46:47], v112, s64, v[140:141]
	v_lshl_add_u64 v[112:113], v[112:113], 0, v[142:143]
	v_mul_f32_e32 v108, v108, v114
	v_mul_f32_e32 v104, v104, v108
	v_add_f32_e32 v108, 1.0, v115
	v_mul_f32_e32 v114, 0xbfb8aa3b, v110
	v_rcp_f32_e32 v108, v108
	v_exp_f32_e32 v114, v114
	v_mul_f32_e32 v115, 0xbfb8aa3b, v111
	v_exp_f32_e32 v115, v115
	v_mul_f32_e32 v108, v109, v108
	v_add_f32_e32 v109, 1.0, v114
	v_rcp_f32_e32 v109, v109
	v_add_f32_e32 v114, 1.0, v115
	v_rcp_f32_e32 v114, v114
	v_mul_f32_e32 v105, v105, v108
	v_mul_f32_e32 v108, v110, v109
	v_mul_f32_e32 v109, 0xbfb8aa3b, v100
	v_exp_f32_e32 v109, v109
	v_mul_f32_e32 v106, v106, v108
	v_mul_f32_e32 v108, v111, v114
	v_mul_f32_e32 v107, v107, v108
	v_cvt_pk_bf16_f32 v104, v104, v105
	v_cvt_pk_bf16_f32 v105, v106, v107
	v_add_f32_e32 v106, 1.0, v109
	v_rcp_f32_e32 v106, v106
	v_mul_f32_e32 v107, 0xbfb8aa3b, v101
	v_exp_f32_e32 v107, v107
	global_store_dwordx2 v[112:113], v[104:105], off
	v_mul_f32_e32 v100, v100, v106
	v_mul_f32_e32 v96, v96, v100
	v_add_f32_e32 v100, 1.0, v107
	v_mul_f32_e32 v104, 0xbfb8aa3b, v102
	v_rcp_f32_e32 v100, v100
	v_exp_f32_e32 v104, v104
	v_mul_f32_e32 v105, 0xbfb8aa3b, v103
	v_exp_f32_e32 v105, v105
	v_mul_f32_e32 v100, v101, v100
	v_add_f32_e32 v101, 1.0, v104
	v_rcp_f32_e32 v101, v101
	v_add_f32_e32 v104, 1.0, v105
	v_rcp_f32_e32 v104, v104
	v_mul_f32_e32 v97, v97, v100
	v_mul_f32_e32 v100, v102, v101
	v_mul_f32_e32 v98, v98, v100
	v_mul_f32_e32 v100, v103, v104
	v_cvt_pk_bf16_f32 v96, v96, v97
	v_mul_f32_e32 v99, v99, v100
	v_cvt_pk_bf16_f32 v97, v98, v99
	global_store_dwordx2 v[112:113], v[96:97], off offset:128
	v_mul_f32_e32 v96, 0xbfb8aa3b, v92
	v_exp_f32_e32 v98, v96
	v_mul_f32_e32 v99, 0xbfb8aa3b, v93
	v_exp_f32_e32 v99, v99
	v_or_b32_e32 v96, 32, v150
	v_add_f32_e32 v98, 1.0, v98
	v_rcp_f32_e32 v98, v98
	v_mad_i64_i32 v[96:97], s[46:47], v96, s64, v[140:141]
	v_lshl_add_u64 v[96:97], v[96:97], 0, v[142:143]
	v_mul_f32_e32 v92, v92, v98
	v_mul_f32_e32 v88, v88, v92
	v_add_f32_e32 v92, 1.0, v99
	v_mul_f32_e32 v98, 0xbfb8aa3b, v94
	v_rcp_f32_e32 v92, v92
	v_exp_f32_e32 v98, v98
	v_mul_f32_e32 v99, 0xbfb8aa3b, v95
	v_exp_f32_e32 v99, v99
	v_mul_f32_e32 v92, v93, v92
	v_add_f32_e32 v93, 1.0, v98
	v_rcp_f32_e32 v93, v93
	v_add_f32_e32 v98, 1.0, v99
	v_rcp_f32_e32 v98, v98
	v_mul_f32_e32 v89, v89, v92
	v_mul_f32_e32 v92, v94, v93
	v_mul_f32_e32 v93, 0xbfb8aa3b, v84
	v_exp_f32_e32 v93, v93
	v_mul_f32_e32 v90, v90, v92
	v_mul_f32_e32 v92, v95, v98
	v_mul_f32_e32 v91, v91, v92
	v_cvt_pk_bf16_f32 v88, v88, v89
	v_cvt_pk_bf16_f32 v89, v90, v91
	v_add_f32_e32 v90, 1.0, v93
	v_rcp_f32_e32 v90, v90
	v_mul_f32_e32 v91, 0xbfb8aa3b, v85
	v_exp_f32_e32 v91, v91
	global_store_dwordx2 v[96:97], v[88:89], off
	v_mul_f32_e32 v84, v84, v90
	v_mul_f32_e32 v80, v80, v84
	v_add_f32_e32 v84, 1.0, v91
	v_mul_f32_e32 v88, 0xbfb8aa3b, v86
	v_rcp_f32_e32 v84, v84
	v_exp_f32_e32 v88, v88
	v_mul_f32_e32 v89, 0xbfb8aa3b, v87
	v_exp_f32_e32 v89, v89
	v_mul_f32_e32 v84, v85, v84
	v_add_f32_e32 v85, 1.0, v88
	v_rcp_f32_e32 v85, v85
	v_add_f32_e32 v88, 1.0, v89
	v_rcp_f32_e32 v88, v88
	v_mul_f32_e32 v81, v81, v84
	v_mul_f32_e32 v84, v86, v85
	v_mul_f32_e32 v82, v82, v84
	v_mul_f32_e32 v84, v87, v88
	v_cvt_pk_bf16_f32 v80, v80, v81
	v_mul_f32_e32 v83, v83, v84
	v_cvt_pk_bf16_f32 v81, v82, v83
	global_store_dwordx2 v[96:97], v[80:81], off offset:128
	v_mul_f32_e32 v80, 0xbfb8aa3b, v76
	v_exp_f32_e32 v82, v80
	v_mul_f32_e32 v83, 0xbfb8aa3b, v77
	v_exp_f32_e32 v83, v83
	v_or_b32_e32 v80, 48, v150
	v_add_f32_e32 v82, 1.0, v82
	v_rcp_f32_e32 v82, v82
	v_mad_i64_i32 v[80:81], s[46:47], v80, s64, v[140:141]
	v_lshl_add_u64 v[80:81], v[80:81], 0, v[142:143]
	v_mul_f32_e32 v76, v76, v82
	v_mul_f32_e32 v72, v72, v76
	v_add_f32_e32 v76, 1.0, v83
	v_mul_f32_e32 v82, 0xbfb8aa3b, v78
	v_rcp_f32_e32 v76, v76
	v_exp_f32_e32 v82, v82
	v_mul_f32_e32 v83, 0xbfb8aa3b, v79
	v_exp_f32_e32 v83, v83
	v_mul_f32_e32 v76, v77, v76
	v_add_f32_e32 v77, 1.0, v82
	v_rcp_f32_e32 v77, v77
	v_add_f32_e32 v82, 1.0, v83
	v_rcp_f32_e32 v82, v82
	v_mul_f32_e32 v73, v73, v76
	v_mul_f32_e32 v76, v78, v77
	v_mul_f32_e32 v77, 0xbfb8aa3b, v68
	v_exp_f32_e32 v77, v77
	v_mul_f32_e32 v74, v74, v76
	v_mul_f32_e32 v76, v79, v82
	v_mul_f32_e32 v75, v75, v76
	v_cvt_pk_bf16_f32 v72, v72, v73
	v_cvt_pk_bf16_f32 v73, v74, v75
	v_add_f32_e32 v74, 1.0, v77
	v_rcp_f32_e32 v74, v74
	v_mul_f32_e32 v75, 0xbfb8aa3b, v69
	v_exp_f32_e32 v75, v75
	global_store_dwordx2 v[80:81], v[72:73], off
	v_mul_f32_e32 v68, v68, v74
	v_mul_f32_e32 v64, v64, v68
	v_add_f32_e32 v68, 1.0, v75
	v_mul_f32_e32 v72, 0xbfb8aa3b, v70
	v_rcp_f32_e32 v68, v68
	v_exp_f32_e32 v72, v72
	v_mul_f32_e32 v73, 0xbfb8aa3b, v71
	v_exp_f32_e32 v73, v73
	v_mul_f32_e32 v68, v69, v68
	v_add_f32_e32 v69, 1.0, v72
	v_rcp_f32_e32 v69, v69
	v_add_f32_e32 v72, 1.0, v73
	v_rcp_f32_e32 v72, v72
	v_mul_f32_e32 v65, v65, v68
	v_mul_f32_e32 v68, v70, v69
	v_mul_f32_e32 v66, v66, v68
	v_mul_f32_e32 v68, v71, v72
	v_cvt_pk_bf16_f32 v64, v64, v65
	v_mul_f32_e32 v67, v67, v68
	v_cvt_pk_bf16_f32 v65, v66, v67
	global_store_dwordx2 v[80:81], v[64:65], off offset:128
	v_mul_f32_e32 v64, 0xbfb8aa3b, v60
	v_exp_f32_e32 v66, v64
	v_mul_f32_e32 v67, 0xbfb8aa3b, v61
	v_exp_f32_e32 v67, v67
	v_add_u32_e32 v64, 0x80, v150
	v_add_f32_e32 v66, 1.0, v66
	v_rcp_f32_e32 v66, v66
	v_mad_i64_i32 v[64:65], s[46:47], v64, s64, v[140:141]
	v_lshl_add_u64 v[64:65], v[64:65], 0, v[142:143]
	v_mul_f32_e32 v60, v60, v66
	v_mul_f32_e32 v56, v56, v60
	v_add_f32_e32 v60, 1.0, v67
	v_mul_f32_e32 v66, 0xbfb8aa3b, v62
	v_rcp_f32_e32 v60, v60
	v_exp_f32_e32 v66, v66
	v_mul_f32_e32 v67, 0xbfb8aa3b, v63
	v_exp_f32_e32 v67, v67
	v_mul_f32_e32 v60, v61, v60
	v_add_f32_e32 v61, 1.0, v66
	v_rcp_f32_e32 v61, v61
	v_add_f32_e32 v66, 1.0, v67
	v_rcp_f32_e32 v66, v66
	v_mul_f32_e32 v57, v57, v60
	v_mul_f32_e32 v60, v62, v61
	v_mul_f32_e32 v61, 0xbfb8aa3b, v52
	v_exp_f32_e32 v61, v61
	v_mul_f32_e32 v58, v58, v60
	v_mul_f32_e32 v60, v63, v66
	v_mul_f32_e32 v59, v59, v60
	v_cvt_pk_bf16_f32 v56, v56, v57
	v_cvt_pk_bf16_f32 v57, v58, v59
	v_add_f32_e32 v58, 1.0, v61
	v_rcp_f32_e32 v58, v58
	v_mul_f32_e32 v59, 0xbfb8aa3b, v53
	v_exp_f32_e32 v59, v59
	global_store_dwordx2 v[64:65], v[56:57], off
	v_mul_f32_e32 v52, v52, v58
	v_mul_f32_e32 v48, v48, v52
	v_add_f32_e32 v52, 1.0, v59
	v_mul_f32_e32 v56, 0xbfb8aa3b, v54
	v_rcp_f32_e32 v52, v52
	v_exp_f32_e32 v56, v56
	v_mul_f32_e32 v57, 0xbfb8aa3b, v55
	v_exp_f32_e32 v57, v57
	v_mul_f32_e32 v52, v53, v52
	v_add_f32_e32 v53, 1.0, v56
	v_rcp_f32_e32 v53, v53
	v_add_f32_e32 v56, 1.0, v57
	v_rcp_f32_e32 v56, v56
	v_mul_f32_e32 v49, v49, v52
	v_mul_f32_e32 v52, v54, v53
	v_mul_f32_e32 v50, v50, v52
	v_mul_f32_e32 v52, v55, v56
	v_cvt_pk_bf16_f32 v48, v48, v49
	v_mul_f32_e32 v51, v51, v52
	v_cvt_pk_bf16_f32 v49, v50, v51
	global_store_dwordx2 v[64:65], v[48:49], off offset:128
	v_mul_f32_e32 v48, 0xbfb8aa3b, v44
	v_exp_f32_e32 v50, v48
	v_mul_f32_e32 v51, 0xbfb8aa3b, v45
	v_exp_f32_e32 v51, v51
	v_add_u32_e32 v48, 0x90, v150
	v_add_f32_e32 v50, 1.0, v50
	v_rcp_f32_e32 v50, v50
	v_mad_i64_i32 v[48:49], s[46:47], v48, s64, v[140:141]
	v_lshl_add_u64 v[48:49], v[48:49], 0, v[142:143]
	v_mul_f32_e32 v44, v44, v50
	v_mul_f32_e32 v40, v40, v44
	v_add_f32_e32 v44, 1.0, v51
	v_mul_f32_e32 v50, 0xbfb8aa3b, v46
	v_rcp_f32_e32 v44, v44
	v_exp_f32_e32 v50, v50
	v_mul_f32_e32 v51, 0xbfb8aa3b, v47
	v_exp_f32_e32 v51, v51
	v_mul_f32_e32 v44, v45, v44
	v_add_f32_e32 v45, 1.0, v50
	v_rcp_f32_e32 v45, v45
	v_add_f32_e32 v50, 1.0, v51
	v_rcp_f32_e32 v50, v50
	v_mul_f32_e32 v41, v41, v44
	v_mul_f32_e32 v44, v46, v45
	v_mul_f32_e32 v45, 0xbfb8aa3b, v36
	v_exp_f32_e32 v45, v45
	v_mul_f32_e32 v42, v42, v44
	v_mul_f32_e32 v44, v47, v50
	v_mul_f32_e32 v43, v43, v44
	v_cvt_pk_bf16_f32 v40, v40, v41
	v_cvt_pk_bf16_f32 v41, v42, v43
	v_add_f32_e32 v42, 1.0, v45
	v_rcp_f32_e32 v42, v42
	v_mul_f32_e32 v43, 0xbfb8aa3b, v37
	v_exp_f32_e32 v43, v43
	global_store_dwordx2 v[48:49], v[40:41], off
	v_mul_f32_e32 v36, v36, v42
	v_mul_f32_e32 v32, v32, v36
	v_add_f32_e32 v36, 1.0, v43
	v_mul_f32_e32 v40, 0xbfb8aa3b, v38
	v_rcp_f32_e32 v36, v36
	v_exp_f32_e32 v40, v40
	v_mul_f32_e32 v41, 0xbfb8aa3b, v39
	v_exp_f32_e32 v41, v41
	v_mul_f32_e32 v36, v37, v36
	v_add_f32_e32 v37, 1.0, v40
	v_rcp_f32_e32 v37, v37
	v_add_f32_e32 v40, 1.0, v41
	v_rcp_f32_e32 v40, v40
	v_mul_f32_e32 v33, v33, v36
	v_mul_f32_e32 v36, v38, v37
	v_mul_f32_e32 v34, v34, v36
	v_mul_f32_e32 v36, v39, v40
	v_cvt_pk_bf16_f32 v32, v32, v33
	v_mul_f32_e32 v35, v35, v36
	v_cvt_pk_bf16_f32 v33, v34, v35
	global_store_dwordx2 v[48:49], v[32:33], off offset:128
	v_mul_f32_e32 v32, 0xbfb8aa3b, v28
	v_exp_f32_e32 v34, v32
	v_mul_f32_e32 v35, 0xbfb8aa3b, v29
	v_exp_f32_e32 v35, v35
	v_add_u32_e32 v32, 0xa0, v150
	v_add_f32_e32 v34, 1.0, v34
	v_rcp_f32_e32 v34, v34
	v_mad_i64_i32 v[32:33], s[46:47], v32, s64, v[140:141]
	v_lshl_add_u64 v[32:33], v[32:33], 0, v[142:143]
	v_mul_f32_e32 v28, v28, v34
	v_mul_f32_e32 v24, v24, v28
	v_add_f32_e32 v28, 1.0, v35
	v_mul_f32_e32 v34, 0xbfb8aa3b, v30
	v_rcp_f32_e32 v28, v28
	v_exp_f32_e32 v34, v34
	v_mul_f32_e32 v35, 0xbfb8aa3b, v31
	v_exp_f32_e32 v35, v35
	v_mul_f32_e32 v28, v29, v28
	v_add_f32_e32 v29, 1.0, v34
	v_rcp_f32_e32 v29, v29
	v_add_f32_e32 v34, 1.0, v35
	v_rcp_f32_e32 v34, v34
	v_mul_f32_e32 v25, v25, v28
	v_mul_f32_e32 v28, v30, v29
	v_mul_f32_e32 v29, 0xbfb8aa3b, v20
	v_exp_f32_e32 v29, v29
	v_mul_f32_e32 v26, v26, v28
	v_mul_f32_e32 v28, v31, v34
	v_mul_f32_e32 v27, v27, v28
	v_cvt_pk_bf16_f32 v24, v24, v25
	v_cvt_pk_bf16_f32 v25, v26, v27
	v_add_f32_e32 v26, 1.0, v29
	v_rcp_f32_e32 v26, v26
	v_mul_f32_e32 v27, 0xbfb8aa3b, v21
	v_exp_f32_e32 v27, v27
	global_store_dwordx2 v[32:33], v[24:25], off
	v_mul_f32_e32 v20, v20, v26
	v_mul_f32_e32 v16, v16, v20
	v_add_f32_e32 v20, 1.0, v27
	v_mul_f32_e32 v24, 0xbfb8aa3b, v22
	v_rcp_f32_e32 v20, v20
	v_exp_f32_e32 v24, v24
	v_mul_f32_e32 v25, 0xbfb8aa3b, v23
	v_exp_f32_e32 v25, v25
	v_mul_f32_e32 v20, v21, v20
	v_add_f32_e32 v21, 1.0, v24
	v_rcp_f32_e32 v21, v21
	v_add_f32_e32 v24, 1.0, v25
	v_rcp_f32_e32 v24, v24
	v_mul_f32_e32 v17, v17, v20
	v_mul_f32_e32 v20, v22, v21
	v_mul_f32_e32 v18, v18, v20
	v_mul_f32_e32 v20, v23, v24
	v_cvt_pk_bf16_f32 v16, v16, v17
	v_mul_f32_e32 v19, v19, v20
	v_cvt_pk_bf16_f32 v17, v18, v19
	global_store_dwordx2 v[32:33], v[16:17], off offset:128
	v_mul_f32_e32 v16, 0xbfb8aa3b, v12
	v_exp_f32_e32 v18, v16
	v_mul_f32_e32 v19, 0xbfb8aa3b, v13
	v_exp_f32_e32 v19, v19
	v_add_u32_e32 v16, 0xb0, v150
	v_add_f32_e32 v18, 1.0, v18
	v_rcp_f32_e32 v18, v18
	v_mad_i64_i32 v[16:17], s[46:47], v16, s64, v[140:141]
	v_lshl_add_u64 v[16:17], v[16:17], 0, v[142:143]
	v_mul_f32_e32 v12, v12, v18
	v_mul_f32_e32 v8, v8, v12
	v_add_f32_e32 v12, 1.0, v19
	v_mul_f32_e32 v18, 0xbfb8aa3b, v14
	v_rcp_f32_e32 v12, v12
	v_exp_f32_e32 v18, v18
	v_mul_f32_e32 v19, 0xbfb8aa3b, v15
	v_exp_f32_e32 v19, v19
	v_mul_f32_e32 v12, v13, v12
	v_add_f32_e32 v13, 1.0, v18
	v_rcp_f32_e32 v13, v13
	v_add_f32_e32 v18, 1.0, v19
	v_rcp_f32_e32 v18, v18
	v_mul_f32_e32 v9, v9, v12
	v_mul_f32_e32 v12, v14, v13
	v_mul_f32_e32 v13, 0xbfb8aa3b, v4
	v_exp_f32_e32 v13, v13
	v_mul_f32_e32 v10, v10, v12
	v_mul_f32_e32 v12, v15, v18
	v_mul_f32_e32 v11, v11, v12
	v_cvt_pk_bf16_f32 v8, v8, v9
	v_cvt_pk_bf16_f32 v9, v10, v11
	v_add_f32_e32 v10, 1.0, v13
	v_rcp_f32_e32 v10, v10
	v_mul_f32_e32 v11, 0xbfb8aa3b, v5
	v_exp_f32_e32 v11, v11
	global_store_dwordx2 v[16:17], v[8:9], off
	v_mul_f32_e32 v4, v4, v10
	v_mul_f32_e32 v0, v0, v4
	v_add_f32_e32 v4, 1.0, v11
	v_mul_f32_e32 v8, 0xbfb8aa3b, v6
	v_rcp_f32_e32 v4, v4
	v_exp_f32_e32 v8, v8
	v_mul_f32_e32 v9, 0xbfb8aa3b, v7
	v_exp_f32_e32 v9, v9
	v_mul_f32_e32 v4, v5, v4
	v_add_f32_e32 v5, 1.0, v8
	v_rcp_f32_e32 v5, v5
	v_add_f32_e32 v8, 1.0, v9
	v_rcp_f32_e32 v8, v8
	v_mul_f32_e32 v1, v1, v4
	v_mul_f32_e32 v4, v6, v5
	v_mul_f32_e32 v2, v2, v4
	v_mul_f32_e32 v4, v7, v8
	s_andn2_b64 vcc, exec, s[8:9]
	s_mov_b64 s[8:9], -1
	v_mul_f32_e32 v3, v3, v4
	v_cvt_pk_bf16_f32 v0, v0, v1
	v_cvt_pk_bf16_f32 v1, v2, v3
	global_store_dwordx2 v[16:17], v[0:1], off offset:128
	s_cbranch_vccnz .LBB0_1430
	s_andn2_b64 vcc, exec, s[0:1]
	s_cbranch_vccnz .LBB0_1429
	s_barrier
	s_branch .LBB0_1429

.LBB0_1517:
	v_lshl_add_u32 v152, s72, 8, v146
	v_lshl_or_b32 v144, s73, 8, v148
	v_ashrrev_i32_e32 v145, 31, v144
	v_ashrrev_i32_e32 v153, 31, v152
	v_lshl_add_u64 v[154:155], v[144:145], 1, s[24:25]
	v_lshlrev_b64 v[144:145], 11, v[152:153]
	v_lshl_add_u64 v[144:145], v[154:155], 0, v[144:145]
	s_nop 15
	s_nop 7
	v_cvt_pk_bf16_f32 v124, v124, v125
	v_cvt_pk_bf16_f32 v125, v126, v127
	v_cvt_pk_bf16_f32 v126, v120, v121
	v_cvt_pk_bf16_f32 v127, v122, v123
	global_store_dwordx4 v[144:145], v[124:127], off
	v_cvt_pk_bf16_f32 v112, v112, v113
	v_cvt_pk_bf16_f32 v113, v114, v115
	v_cvt_pk_bf16_f32 v114, v104, v105
	v_or_b32_e32 v104, 16, v152
	v_ashrrev_i32_e32 v105, 31, v104
	v_lshlrev_b64 v[104:105], 11, v[104:105]
	v_cvt_pk_bf16_f32 v115, v106, v107
	global_store_dwordx4 v[144:145], v[112:115], off offset:256
	s_nop 1
	v_lshl_add_u64 v[112:113], v[154:155], 0, v[104:105]
	v_cvt_pk_bf16_f32 v104, v116, v117
	v_cvt_pk_bf16_f32 v105, v118, v119
	v_cvt_pk_bf16_f32 v106, v108, v109
	v_cvt_pk_bf16_f32 v107, v110, v111
	global_store_dwordx4 v[112:113], v[104:107], off
	v_cvt_pk_bf16_f32 v96, v96, v97
	v_cvt_pk_bf16_f32 v97, v98, v99
	v_cvt_pk_bf16_f32 v98, v88, v89
	v_or_b32_e32 v88, 32, v152
	v_ashrrev_i32_e32 v89, 31, v88
	v_lshlrev_b64 v[88:89], 11, v[88:89]
	v_cvt_pk_bf16_f32 v99, v90, v91
	global_store_dwordx4 v[112:113], v[96:99], off offset:256
	s_nop 1
	v_lshl_add_u64 v[96:97], v[154:155], 0, v[88:89]
	v_cvt_pk_bf16_f32 v88, v100, v101
	v_cvt_pk_bf16_f32 v89, v102, v103
	v_cvt_pk_bf16_f32 v90, v92, v93
	v_cvt_pk_bf16_f32 v91, v94, v95
	global_store_dwordx4 v[96:97], v[88:91], off
	v_cvt_pk_bf16_f32 v80, v80, v81
	v_cvt_pk_bf16_f32 v81, v82, v83
	v_cvt_pk_bf16_f32 v82, v72, v73
	v_or_b32_e32 v72, 48, v152
	s_and_b64 vcc, exec, s[12:13]
	s_cbranch_vccz .Lxb_12
	s_barrier
.Lxb_12:
	v_ashrrev_i32_e32 v73, 31, v72
	v_lshlrev_b64 v[72:73], 11, v[72:73]
	v_cvt_pk_bf16_f32 v83, v74, v75
	global_store_dwordx4 v[96:97], v[80:83], off offset:256
	s_nop 1
	v_lshl_add_u64 v[80:81], v[154:155], 0, v[72:73]
	v_cvt_pk_bf16_f32 v72, v84, v85
	v_cvt_pk_bf16_f32 v73, v86, v87
	v_cvt_pk_bf16_f32 v74, v76, v77
	v_cvt_pk_bf16_f32 v75, v78, v79
	global_store_dwordx4 v[80:81], v[72:75], off
	v_cvt_pk_bf16_f32 v68, v68, v69
	v_cvt_pk_bf16_f32 v69, v70, v71
	v_cvt_pk_bf16_f32 v70, v64, v65
	v_cvt_pk_bf16_f32 v71, v66, v67
	global_store_dwordx4 v[80:81], v[68:71], off offset:256
	v_cvt_pk_bf16_f32 v60, v60, v61
	v_cvt_pk_bf16_f32 v61, v62, v63
	v_cvt_pk_bf16_f32 v62, v56, v57
	v_add_co_u32_e32 v56, vcc, s66, v144
	v_lshl_add_u64 v[64:65], v[144:145], 0, s[16:17]
	s_nop 0
	v_addc_co_u32_e32 v57, vcc, 0, v145, vcc
	v_cvt_pk_bf16_f32 v63, v58, v59
	global_store_dwordx4 v[56:57], v[60:63], off
	v_cvt_pk_bf16_f32 v48, v48, v49
	v_cvt_pk_bf16_f32 v49, v50, v51
	v_cvt_pk_bf16_f32 v50, v40, v41
	v_cvt_pk_bf16_f32 v51, v42, v43
	global_store_dwordx4 v[64:65], v[48:51], off offset:256
	v_cvt_pk_bf16_f32 v40, v52, v53
	v_cvt_pk_bf16_f32 v41, v54, v55
	v_cvt_pk_bf16_f32 v42, v44, v45
	v_add_co_u32_e32 v44, vcc, s67, v144
	s_nop 0
	v_lshl_add_u64 v[48:49], v[144:145], 0, s[18:19]
	v_addc_co_u32_e32 v45, vcc, 0, v145, vcc
	v_cvt_pk_bf16_f32 v43, v46, v47
	global_store_dwordx4 v[44:45], v[40:43], off
	v_cvt_pk_bf16_f32 v32, v32, v33
	v_cvt_pk_bf16_f32 v33, v34, v35
	v_cvt_pk_bf16_f32 v34, v24, v25
	v_cvt_pk_bf16_f32 v35, v26, v27
	global_store_dwordx4 v[48:49], v[32:35], off offset:256
	v_cvt_pk_bf16_f32 v24, v36, v37
	v_cvt_pk_bf16_f32 v25, v38, v39
	v_cvt_pk_bf16_f32 v26, v28, v29
	v_add_co_u32_e32 v28, vcc, s68, v144
	s_nop 0
	v_lshl_add_u64 v[32:33], v[144:145], 0, s[30:31]
	v_addc_co_u32_e32 v29, vcc, 0, v145, vcc
	v_cvt_pk_bf16_f32 v27, v30, v31
	global_store_dwordx4 v[28:29], v[24:27], off
	v_cvt_pk_bf16_f32 v16, v16, v17
	v_cvt_pk_bf16_f32 v17, v18, v19
	v_cvt_pk_bf16_f32 v18, v8, v9
	v_cvt_pk_bf16_f32 v19, v10, v11
	global_store_dwordx4 v[32:33], v[16:19], off offset:256
	v_cvt_pk_bf16_f32 v8, v20, v21
	v_cvt_pk_bf16_f32 v9, v22, v23
	v_cvt_pk_bf16_f32 v10, v12, v13
	v_add_co_u32_e32 v12, vcc, s69, v144
	s_nop 0
	v_lshl_add_u64 v[16:17], v[144:145], 0, s[36:37]
	v_addc_co_u32_e32 v13, vcc, 0, v145, vcc
	s_and_b64 vcc, exec, s[6:7]
	s_mov_b64 s[6:7], -1
	v_cvt_pk_bf16_f32 v11, v14, v15
	global_store_dwordx4 v[12:13], v[8:11], off
	v_cvt_pk_bf16_f32 v4, v4, v5
	v_cvt_pk_bf16_f32 v5, v6, v7
	v_cvt_pk_bf16_f32 v6, v0, v1
	v_cvt_pk_bf16_f32 v7, v2, v3
	global_store_dwordx4 v[16:17], v[4:7], off offset:256
	s_cbranch_vccnz .LBB0_1502
	s_andn2_b64 vcc, exec, s[0:1]
	s_cbranch_vccnz .LBB0_1501
	s_barrier
	s_branch .LBB0_1501
